# 64-byte instruction-fetch alignment of the 25 MFMA hot-loop heads (.p2align 6) on top of v13
# baseline (speedup 1.0000x reference)
; #define PG8_STAGE(bufoff, gbase, voff) do { _Pragma("unroll") for (int _i = 0; _i < 2; ++_i) \
;         __builtin_amdgcn_global_load_lds((const unsigned*)((const char*)(gbase) + (voff)[_i]), (PG8_LAS unsigned*)(lds + (bufoff) + ldsw + _i * 8192), 16, 0, 0); } while (0)
; #define PG8_WAIT_V(n) asm volatile("s_waitcnt vmcnt(" #n ")" ::: "memory")
; #define PG8_BAR __builtin_amdgcn_s_barrier()
; template <class Epi, class Sched, bool ALIGN_EPI = false, bool SP2 = false>
; __device__ __forceinline__ void gemm_phase(PG8_LAS unsigned char* lds, const Gemm g, const Sched& S, const Epi& E) {
;     ...
;     if constexpr (SP2) {
;         PG8_STAGE(PG8_SB(0, 0), cB, voffB); PG8_STAGE(PG8_SB(0, 1), cB + hstep, voffB); PG8_STAGE(PG8_SA(0, 0), cA, voffA); PG8_STAGE(PG8_SA(0, 1), cA + hstep, voffA);
;         if (wr == 1) PG8_BAR;
;         PG8_WAIT_V(2); PG8_BAR;
;         PG8_STAGE(PG8_SB(1, 0), cB + kstep, voffB); PG8_STAGE(PG8_SA(1, 0), cA + kstep, voffA); PG8_STAGE(PG8_SB(1, 1), cB + hstep + kstep, voffB);
;         PG8_WAIT_V(6); PG8_BAR;
.LBB0_128:
	s_lshl_b32 s3, s12, 5
	s_mov_b64 s[12:13], 0x80
	s_add_i32 m0, s72, 0x18000
	v_lshl_add_u64 v[6:7], v[6:7], 0, s[12:13]
	s_lshl_b32 s1, s15, 13
	s_and_b32 s3, s3, 0x60
	s_waitcnt vmcnt(2)
	s_barrier
	global_load_lds_dwordx4 v[6:7], off
	v_lshl_add_u64 v[4:5], v[4:5], 0, s[12:13]
	s_add_i32 m0, s72, 0x1a000
	s_add_i32 s78, s72, 0x8000
	s_add_i32 s79, s72, 0xa000
	global_load_lds_dwordx4 v[4:5], off
	v_lshl_add_u64 v[0:1], v[0:1], 0, s[12:13]
	s_mov_b32 m0, s78
	s_add_u32 s24, s64, 0x40080
	global_load_lds_dwordx4 v[0:1], off
	v_lshl_add_u64 v[0:1], v[2:3], 0, s[12:13]
	s_mov_b32 m0, s79
	s_addc_u32 s25, s65, 0
	global_load_lds_dwordx4 v[0:1], off
	s_add_i32 m0, s72, 0x1c000
	v_lshl_add_u64 v[0:1], s[24:25], 0, v[178:179]
	global_load_lds_dwordx4 v[0:1], off
	v_lshl_add_u64 v[0:1], s[24:25], 0, v[182:183]
	s_add_i32 m0, s72, 0x1e000
	v_lshlrev_b32_e32 v2, 11, v197
	global_load_lds_dwordx4 v[0:1], off
	v_lshlrev_b32_e32 v1, 2, v189
	v_lshl_or_b32 v0, v189, 6, v190
	v_and_b32_e32 v1, 32, v1
	v_bitop3_b32 v0, v0, s1, v1 bitop3:0xde
	v_lshlrev_b32_e32 v1, 8, v192
	v_and_b32_e32 v1, 0x38000, v1
	v_or3_b32 v1, v186, v1, v2
	s_cmpk_lt_u32 s14, 0x100
	v_add_u32_e32 v130, v1, v187
	v_lshlrev_b32_e32 v1, 4, v198
	v_lshl_or_b32 v145, s15, 6, v189
	v_lshl_or_b32 v146, s3, 7, v191
	s_waitcnt vmcnt(6)
	s_cselect_b64 s[14:15], -1, 0
	v_and_b32_e32 v1, 0x78000, v1
	s_add_i32 s86, 0, 0x10000
	v_or3_b32 v1, v186, v1, v2
	v_add_u32_e32 v155, s86, v146
	s_add_i32 s80, 0, 0x14000
	s_add_i32 s86, s86, s69
	v_or_b32_e32 v147, s3, v188
	v_or_b32_e32 v148, 16, v145
	v_or_b32_e32 v149, 32, v145
	v_or_b32_e32 v150, 48, v145
	v_add_u32_e32 v151, 0x80, v145
	v_add_u32_e32 v152, 0x90, v145
	v_add_u32_e32 v153, 0xa0, v145
	v_add_u32_e32 v154, 0xb0, v145
	v_mov_b32_e32 v131, v129
	v_add_u32_e32 v132, v1, v187
	v_mov_b32_e32 v133, v129
	v_add_u32_e32 v156, s80, v146
	v_add_u32_e32 v157, 0, v0
	s_movk_i32 s81, 0xc00
	s_movk_i32 s82, 0x3ff
	s_movk_i32 s83, 0xc10
	s_add_i32 s84, s72, 0xc000
	s_add_i32 s85, s72, 0xe000
	s_add_i32 s87, s86, 0x2000
	s_barrier
	s_branch .LBB0_131
	.p2align 6
.LBB0_129:
	s_mov_b64 s[0:1], 0
	.p2align 6

; template <class Epi, class Sched, bool ALIGN_EPI = false, bool SP2 = false>
; __device__ __forceinline__ void gemm_phase(PG8_LAS unsigned char* lds, const Gemm g, const Sched& S, const Epi& E) {
;     ...
;         const bool has_next = S.next(ui + 1, nxt);
;         const char* nA = has_next ? (const char*)g.A + (size_t)nxt.pm * tstep : cA; const char* nB = has_next ? (const char*)g.Bt + (size_t)nxt.pn * tstep : cB;
;     ...
; #pragma unroll
;         for (int a = 0; a < 2; ++a)
; #pragma unroll
;             for (int b = 0; b < 2; ++b)
; #pragma unroll
;                 for (int m = 0; m < 4; ++m)
; #pragma unroll
;                     for (int n = 0; n < 2; ++n) acc[a][b][m][n] = (f32x4){0.f, 0.f, 0.f, 0.f};
;         cur = nxt; cA = nA; cB = nB; ++ui;
.LBB0_133:
	s_ashr_i32 s25, s24, 31
	s_lshl_b64 s[34:35], s[24:25], 19
	s_add_u32 s34, s58, s34
	s_addc_u32 s35, s59, s35
	s_and_b64 s[60:61], s[56:57], exec
	s_cselect_b32 s1, s35, s63
	s_cselect_b32 s3, s34, s62
	s_ashr_i32 s27, s26, 31
	s_lshl_b64 s[60:61], s[26:27], 19
	s_add_u32 s60, s28, s60
	s_addc_u32 s61, s29, s61
	s_and_b64 s[66:67], s[56:57], exec
	s_cselect_b32 s25, s61, s65
	s_cselect_b32 s27, s60, s64
	s_add_u32 s62, s62, 0x40080
	s_addc_u32 s63, s63, 0
	s_add_u32 s88, s64, 0x100
	v_mov_b32_e32 v0, 0
	s_addc_u32 s89, s65, 0
	s_mov_b32 s90, -2
	v_mov_b32_e32 v1, v0
	v_mov_b32_e32 v2, v0
	v_mov_b32_e32 v3, v0
	v_mov_b32_e32 v4, v0
	v_mov_b32_e32 v5, v0
	v_mov_b32_e32 v6, v0
	v_mov_b32_e32 v7, v0
	v_mov_b32_e32 v16, v0
	v_mov_b32_e32 v17, v0
	v_mov_b32_e32 v18, v0
	v_mov_b32_e32 v19, v0
	v_mov_b32_e32 v20, v0
	v_mov_b32_e32 v21, v0
	v_mov_b32_e32 v22, v0
	v_mov_b32_e32 v23, v0
	v_mov_b32_e32 v32, v0
	v_mov_b32_e32 v33, v0
	v_mov_b32_e32 v34, v0
	v_mov_b32_e32 v35, v0
	v_mov_b32_e32 v36, v0
	v_mov_b32_e32 v37, v0
	v_mov_b32_e32 v38, v0
	v_mov_b32_e32 v39, v0
	v_mov_b32_e32 v48, v0
	v_mov_b32_e32 v49, v0
	v_mov_b32_e32 v50, v0
	v_mov_b32_e32 v51, v0
	v_mov_b32_e32 v52, v0
	v_mov_b32_e32 v53, v0
	v_mov_b32_e32 v54, v0
	v_mov_b32_e32 v55, v0
	v_mov_b32_e32 v8, v0
	v_mov_b32_e32 v9, v0
	v_mov_b32_e32 v10, v0
	v_mov_b32_e32 v11, v0
	v_mov_b32_e32 v12, v0
	v_mov_b32_e32 v13, v0
	v_mov_b32_e32 v14, v0
	v_mov_b32_e32 v15, v0
	v_mov_b32_e32 v24, v0
	v_mov_b32_e32 v25, v0
	v_mov_b32_e32 v26, v0
	v_mov_b32_e32 v27, v0
	v_mov_b32_e32 v28, v0
	v_mov_b32_e32 v29, v0
	v_mov_b32_e32 v30, v0
	v_mov_b32_e32 v31, v0
	v_mov_b32_e32 v40, v0
	v_mov_b32_e32 v41, v0
	v_mov_b32_e32 v42, v0
	v_mov_b32_e32 v43, v0
	v_mov_b32_e32 v44, v0
	v_mov_b32_e32 v45, v0
	v_mov_b32_e32 v46, v0
	v_mov_b32_e32 v47, v0
	v_mov_b32_e32 v56, v0
	v_mov_b32_e32 v57, v0
	v_mov_b32_e32 v58, v0
	v_mov_b32_e32 v59, v0
	v_mov_b32_e32 v60, v0
	v_mov_b32_e32 v61, v0
	v_mov_b32_e32 v62, v0
	v_mov_b32_e32 v63, v0
	v_mov_b32_e32 v64, v0
	v_mov_b32_e32 v65, v0
	v_mov_b32_e32 v66, v0
	v_mov_b32_e32 v67, v0
	v_mov_b32_e32 v68, v0
	v_mov_b32_e32 v69, v0
	v_mov_b32_e32 v70, v0
	v_mov_b32_e32 v71, v0
	v_mov_b32_e32 v80, v0
	v_mov_b32_e32 v81, v0
	v_mov_b32_e32 v82, v0
	v_mov_b32_e32 v83, v0
	v_mov_b32_e32 v84, v0
	v_mov_b32_e32 v85, v0
	v_mov_b32_e32 v86, v0
	v_mov_b32_e32 v87, v0
	v_mov_b32_e32 v96, v0
	v_mov_b32_e32 v97, v0
	v_mov_b32_e32 v98, v0
	v_mov_b32_e32 v99, v0
	v_mov_b32_e32 v100, v0
	v_mov_b32_e32 v101, v0
	v_mov_b32_e32 v102, v0
	v_mov_b32_e32 v103, v0
	v_mov_b32_e32 v112, v0
	v_mov_b32_e32 v113, v0
	v_mov_b32_e32 v114, v0
	v_mov_b32_e32 v115, v0
	v_mov_b32_e32 v116, v0
	v_mov_b32_e32 v117, v0
	v_mov_b32_e32 v118, v0
	v_mov_b32_e32 v119, v0
	v_mov_b32_e32 v72, v0
	v_mov_b32_e32 v73, v0
	v_mov_b32_e32 v74, v0
	v_mov_b32_e32 v75, v0
	v_mov_b32_e32 v76, v0
	v_mov_b32_e32 v77, v0
	v_mov_b32_e32 v78, v0
	v_mov_b32_e32 v79, v0
	v_mov_b32_e32 v88, v0
	v_mov_b32_e32 v89, v0
	v_mov_b32_e32 v90, v0
	v_mov_b32_e32 v91, v0
	v_mov_b32_e32 v92, v0
	v_mov_b32_e32 v93, v0
	v_mov_b32_e32 v94, v0
	v_mov_b32_e32 v95, v0
	v_mov_b32_e32 v104, v0
	v_mov_b32_e32 v105, v0
	v_mov_b32_e32 v106, v0
	v_mov_b32_e32 v107, v0
	v_mov_b32_e32 v108, v0
	v_mov_b32_e32 v109, v0
	v_mov_b32_e32 v110, v0
	v_mov_b32_e32 v111, v0
	v_mov_b32_e32 v120, v0
	v_mov_b32_e32 v121, v0
	v_mov_b32_e32 v122, v0
	v_mov_b32_e32 v123, v0
	v_mov_b32_e32 v124, v0
	v_mov_b32_e32 v125, v0
	v_mov_b32_e32 v126, v0
	v_mov_b32_e32 v127, v0
	.p2align 6

; DI void run_phase(const Params& p, int ph, char* lds) {
;     ...
;             u32x2 xr[20];
; #pragma unroll
;             for (int r = 0; r < 20; ++r) xr[r] = (u32x2){0u, 0u};
;             if ((int)blockIdx.x < NCHUNK * 4) dn_prep_load(p, blockIdx.x >> 2, blockIdx.x & 3, xr);
;             for (int u = blockIdx.x; u < NCHUNK * 4; u += gridDim.x) {
;                 const int un = u + gridDim.x;
;                 dn_prep_unit(p, u >> 2, u & 3, lds, xr, un < NCHUNK * 4 ? (un >> 2) : -1, un & 3);
;             }
.LBB0_403:
	s_add_u32 s60, s28, 0x25f20000
	s_addc_u32 s61, s29, 0
	s_add_u32 s12, s28, 0x1ff20000
	s_addc_u32 s13, s29, 0
	s_add_u32 s14, s28, 0x7f20000
	s_addc_u32 s15, s29, 0
	s_add_u32 s24, s28, 0x13f20000
	s_addc_u32 s25, s29, 0
	s_add_i32 s2, s6, s7
	s_lshl_b32 s62, s6, 4
	s_lshl_b32 s63, s7, 4
	s_lshl_b32 s64, s2, 7
	s_lshl_b32 s65, s7, 7
	s_mov_b32 s27, 0
	s_mov_b32 s66, 0x3fb8aa3b
	s_mov_b32 s67, 0xc2ce8ed0
	s_mov_b32 s68, 0x42b17218
	v_mov_b32_e32 v142, 0x3ecc95a3
	s_mov_b32 s75, 0x3f317218
	s_mov_b32 s76, 0x33800000
	s_mov_b32 s77, 0xbfb8aa3b
	s_mov_b32 s78, 0x42ce8ed0
	s_mov_b32 s79, 0xc2b17218
	s_add_i32 s80, 0, 0x26400
	v_mov_b32_e32 v94, 0
	s_movk_i32 s81, 0x1000
	s_movk_i32 s82, 0x3000
	s_movk_i32 s83, 0x80
	s_mov_b32 s84, 0x800000
	s_movk_i32 s85, 0x1080
	s_movk_i32 s86, 0x108
	s_movk_i32 s87, 0x180
	s_mov_b32 s88, 0x7ffff800
	s_movk_i32 s89, 0x7c0
	s_movk_i32 s90, 0x800
	s_movk_i32 s91, 0xc00
	s_movk_i32 s92, 0x100
	s_add_i32 s93, 0, 0x11400
	s_add_i32 s94, 0, 0x15400
	s_add_i32 s95, 0, 0x26600
	s_movk_i32 s96, 0x4800
	s_add_i32 s97, 0, 0x1d400
	s_movk_i32 s72, 0x2400
	s_movk_i32 s69, 0x2000
	v_mov_b32_e32 v143, 0x7f800000
	v_mov_b32_e32 v98, 0x3f317218
	v_mbcnt_hi_u32_b32 v145, -1, v144
	v_mov_b32_e32 v146, 0x6000000
	v_mov_b32_e32 v147, 0x4200
	v_mov_b32_e32 v148, 0x8400
	v_mov_b32_e32 v149, 0xcc00
	v_mov_b32_e32 v150, 0x19400
	v_mov_b32_e32 v151, 0x11400
	s_mov_b32 s42, s6
	s_branch .LBB0_405
	.p2align 6

; DI void run_phase(const Params& p, int ph, char* lds) {
;     ...
;     case 3: {
;         unsigned* ctr = (unsigned*)(ws + OFF_CTR);
;         int* item_s = (int*)(lds + LDS_BYTES - 16);
;         const bf16_t* bufA = (const bf16_t*)((char*)p.out + 2 * U1);
;         bf16_t* ao = (bf16_t*)(ws + OFF_MIX);
;         for (;;) {
;             __syncthreads();
;             if (threadIdx.x == 0) *item_s = (int)atomicAdd(ctr, 1u);
;             __syncthreads();
;             const int it = __builtin_amdgcn_readfirstlane(*item_s);
;             if (it >= Q_TOTAL) break;
.LBB0_565:
	s_or_b64 exec, exec, s[2:3]
	s_add_u32 s4, s28, 0x1910000
	s_addc_u32 s5, s29, 0
	s_add_u32 s63, s28, 0x7f20000
	s_addc_u32 s65, s29, 0
	s_add_u32 s74, s28, 0x1ff20000
	s_addc_u32 s75, s29, 0
	s_add_u32 s76, s28, 0x13f20000
	s_addc_u32 s77, s29, 0
	s_add_u32 s78, s28, 0x25f20000
	s_addc_u32 s79, s29, 0
	s_add_u32 s36, s58, 0x6000000
	s_addc_u32 s37, s59, 0
	s_add_u32 s40, s58, 0xc040400
	s_addc_u32 s41, s59, 0
	s_add_i32 s80, 0, 0x27ff0
	s_mov_b32 s13, 0
	v_mov_b32_e32 v185, 0
	v_mov_b32_e32 v177, s80
	s_mov_b32 s81, 0x10000
	s_mov_b64 s[56:57], 0x30000
	s_mov_b32 s82, 0x4138aa3b
	s_mov_b32 s83, 0x20000
	s_mov_b32 s84, 0x30000
	s_mov_b64 s[60:61], 0x40000
	s_brev_b32 s62, 60
	s_mov_b32 s64, 0x358637bd
	s_mov_b32 s85, 0x800000
	s_mov_b32 s86, 0xc800
	s_mov_b32 s87, 0x32220000
	s_movk_i32 s88, 0x108
	s_movk_i32 s89, 0x88
	s_add_i32 s90, 0, 0x12c00
	s_add_i32 s91, 0, 0x1b200
	s_add_i32 s92, 0, 0x16e00
	s_movk_i32 s93, 0x430
	s_mov_b32 s94, 0xea00
	s_movk_i32 s95, 0x440
	v_mbcnt_hi_u32_b32 v203, -1, v144
	v_mov_b32_e32 v179, 0x2100
	v_mov_b32_e32 v181, 0x1100
	s_barrier
	s_branch .LBB0_568
	.p2align 6

; DI int v_st(int k, int c) { const int kk = (k & ~0xC) | ((k & 4) << 1) | ((k & 8) >> 1); return ((kk >> 3) * 4 + (c >> 5)) * 512 + ((kk & 7) * 32 + (c & 31)) * 2; }
; DI int v_rd_base(int lane) { return ((lane & 3) << 3) | (((lane >> 2) & 3) << 6) | (((lane >> 4) & 1) << 5) | (((lane >> 5) & 1) << 8); }
; #define SLOAD(i, k0) do { sr_[i].vs0 = *(const bf16x8*)(&Vh[(long)((k0) + sr) * LDA_ + sc]); sr_[i].vs1 = *(const bf16x8*)(&Vh[(long)((k0) + 32 + sr) * LDA_ + sc]); \
;     sr_[i].ks0 = *(const bf16x8*)(&Kh[(long)((k0) + sr) * LDA_ + sc]); sr_[i].ks1 = *(const bf16x8*)(&Kh[(long)((k0) + 32 + sr) * LDA_ + sc]); } while (0)
; #define SWRITE(b, i) do { *(bf16x8*)(V_lds + (b) * SHM_V + vst0) = sr_[i].vs0;          \
;     *(bf16x8*)(V_lds + (b) * SHM_V + vst1) = sr_[i].vs1; int kc = sc * 2;               \
;     *(bf16x8*)(K_lds + (b) * SHM_K + KSWZ(sr, kc)) = sr_[i].ks0;                       \
;     *(bf16x8*)(K_lds + (b) * SHM_K + KSWZ(32 + sr, kc)) = sr_[i].ks1; } while (0)
; DI void attn_unit(const bf16_t* __restrict__ Qb, const bf16_t* __restrict__ Kh, const bf16_t* __restrict__ Vh, bf16_t* __restrict__ Ob, const float* __restrict__ onw, int seq, char* lds) {
;     int tid_ = threadIdx.x; asm volatile("" : "+v"(tid_));
;     const int tid = tid_, wid = tid >> 6, lane = tid & 63, r32 = lane & 31, hi = lane >> 5;
;     char* V_lds = lds; char* K_lds = lds + 2 * SHM_V;
;     float* wsf = (float*)(lds + 2 * SHM_V + 2 * SHM_K) + wid * 64; float* li_l = wsf; float* al_l = wsf + 32;
;     float m_reg = 0.f, l_reg = 0; f32x16 o[4]; bf16x8 qr[8];
; #pragma unroll
;     for (int d = 0; d < 4; ++d)
; #pragma unroll
;         for (int i = 0; i < 16; ++i) o[d][i] = 0.f;
;     const bf16_t* Qw = Qb + (long)((wid & 3) * 32 + r32) * LDA_ + (wid >> 2) * 128 + hi * 8;
; #pragma unroll
;     for (int d0 = 0; d0 < 8; ++d0) qr[d0] = *(const bf16x8*)(Qw + d0 * 16);
;     const int sr = tid >> 4, sc = (tid & 15) * 8, vst0 = v_st(sr, sc), vst1 = v_st(32 + sr, sc);
;     const int vb0 = (int)(uintptr_t)V_lds + v_rd_base(lane);
;     struct { bf16x8 vs0, vs1, ks0, ks1; } sr_[1];
;     ...
;     f32x16 pA0, pA1, pB0, pB1; float alA, alB; bf16x8 pa0, pa1, pa2, pa3; const int NT = seq / 64;
;     constexpr int SE = 0, SO = 0;
;     SLOAD(SE, 0); asm volatile("s_waitcnt vmcnt(0)" ::: "memory"); SWRITE(0, SE); __syncthreads();
.LBB0_579:
	s_and_b32 s12, s14, 1
	s_lshl_b32 s2, s15, 7
	s_add_u32 s2, s68, s2
	s_addc_u32 s3, s69, 0
	s_lshl_b64 s[66:67], s[2:3], 10
	s_lshl_b64 s[2:3], s[2:3], 11
	s_add_u32 s2, s30, s2
	s_addc_u32 s3, s31, s3
	s_lshl_b32 s72, s12, 8
	s_lshl_b32 s12, s12, 9
	s_add_u32 s2, s2, s12
	s_waitcnt vmcnt(0)
	v_mov_b32_e32 v80, v192
	s_addc_u32 s3, s3, 0
	s_lshl_b64 s[14:15], s[68:69], 11
	s_add_u32 s12, s30, s14
	v_ashrrev_i32_e32 v48, 4, v80
	v_lshlrev_b32_e32 v20, 3, v80
	v_add_u32_e32 v16, 32, v48
	s_addc_u32 s15, s31, s15
	v_and_b32_e32 v0, 0x78, v20
	v_ashrrev_i32_e32 v49, 31, v48
	v_ashrrev_i32_e32 v17, 31, v16
	s_add_u32 s14, s12, s72
	v_lshlrev_b32_e32 v21, 1, v0
	v_lshlrev_b64 v[0:1], 11, v[48:49]
	v_lshlrev_b64 v[4:5], 11, v[16:17]
	s_addc_u32 s15, s15, 0
	v_or_b32_e32 v0, v0, v21
	v_or_b32_e32 v4, v4, v21
	v_lshl_add_u64 v[50:51], s[14:15], 0, v[0:1]
	v_lshl_add_u64 v[12:13], s[14:15], 0, v[4:5]
	s_add_u32 s98, s14, 0x20400
	s_addc_u32 s99, s15, 0
	v_readfirstlane_b32 s100, v80
	v_and_b32_e32 v250, 63, v80
	v_lshrrev_b32_e32 v251, 6, v80
	v_lshrrev_b32_e32 v252, 4, v250
	v_and_b32_e32 v253, 1, v251
	v_lshl_add_u32 v253, v253, 2, v252
	v_and_b32_e32 v246, 15, v250
	v_xor_b32_e32 v246, v246, v253
	v_lshlrev_b32_e32 v246, 4, v246
	v_lshl_add_u32 v252, v251, 2, v252
	v_lshl_add_u32 v246, v252, 11, v246
	v_add_u32_e32 v246, 0x20000, v246
	v_add_u32_e32 v247, 0x10000, v246
	v_bfe_u32 v252, v250, 2, 3
	v_and_b32_e32 v253, 3, v252
	v_lshrrev_b32_e32 v252, 2, v252
	v_lshl_add_u32 v253, v252, 3, v253
	v_bfe_u32 v252, v251, 1, 1
	v_lshl_add_u32 v253, v252, 2, v253
	v_bfe_u32 v252, v251, 2, 1
	v_lshl_add_u32 v253, v252, 4, v253
	v_lshlrev_b32_e32 v248, 11, v253
	v_and_b32_e32 v252, 1, v251
	v_lshlrev_b32_e32 v252, 1, v252
	v_lshrrev_b32_e32 v253, 5, v250
	v_add_u32_e32 v252, v252, v253
	v_and_b32_e32 v253, 3, v250
	v_lshl_add_u32 v252, v252, 2, v253
	v_lshl_add_u32 v248, v252, 4, v248
	v_add_u32_e32 v248, 0x200, v248
	v_add_u32_e32 v249, 0x10000, v248
	s_lshl_b32 s100, s100, 4
	s_add_u32 m0, s100, 0x4000
	s_nop 0
	global_load_lds_dwordx4 v248, s[98:99]
	s_add_u32 m0, s100, 0x6000
	s_nop 0
	global_load_lds_dwordx4 v249, s[98:99]
	s_sub_u32 s98, s98, 0x20000
	s_subb_u32 s99, s99, 0
	s_add_u32 m0, s100, 0xc000
	s_nop 0
	global_load_lds_dwordx4 v246, s[98:99]
	s_add_u32 m0, s100, 0xe000
	s_nop 0
	global_load_lds_dwordx4 v247, s[98:99]
	s_add_u32 s98, s98, 0x20000
	s_addc_u32 s99, s99, 0
	global_load_dwordx4 v[0:3], v[50:51], off offset:1536
	global_load_dwordx4 v[4:7], v[12:13], off offset:1536
	global_load_dwordx4 v[8:11], v[50:51], off offset:1024
	s_nop 0
	global_load_dwordx4 v[12:15], v[12:13], off offset:1024
	v_lshrrev_b32_e32 v17, 1, v80
	v_and_b32_e32 v155, 31, v80
	v_and_b32_e32 v170, 0x60, v17
	v_or_b32_e32 v17, v170, v155
	v_lshlrev_b32_e32 v184, 11, v17
	v_ashrrev_i32_e32 v17, 1, v80
	v_and_b32_e32 v148, 0xffffff80, v17
	v_bfe_u32 v151, v80, 5, 1
	v_lshl_add_u64 v[18:19], s[2:3], 0, v[184:185]
	v_ashrrev_i32_e32 v149, 31, v148
	v_lshl_add_u64 v[18:19], v[148:149], 1, v[18:19]
	v_lshlrev_b32_e32 v184, 4, v151
	v_lshl_add_u64 v[18:19], v[18:19], 0, v[184:185]
	global_load_dwordx4 v[140:143], v[18:19], off
	global_load_dwordx4 v[136:139], v[18:19], off offset:32
	global_load_dwordx4 v[132:135], v[18:19], off offset:64
	global_load_dwordx4 v[128:131], v[18:19], off offset:96
	global_load_dwordx4 v[124:127], v[18:19], off offset:128
	global_load_dwordx4 v[120:123], v[18:19], off offset:160
	global_load_dwordx4 v[116:119], v[18:19], off offset:192
	global_load_dwordx4 v[112:115], v[18:19], off offset:224
	v_and_b32_e32 v22, 0xfffff0, v48
	v_lshlrev_b32_e32 v23, 1, v48
	v_lshrrev_b32_e32 v24, 1, v48
	v_and_b32_e32 v25, 3, v48
	v_and_or_b32 v22, v23, 8, v22
	v_and_or_b32 v23, v24, 4, v25
	v_and_b32_e32 v24, 0xfffff0, v16
	v_lshlrev_b32_e32 v25, 1, v16
	v_and_b32_e32 v17, 0x70, v80
	v_bfe_u32 v20, v20, 5, 2
	v_lshlrev_b32_e32 v26, 8, v48
	v_lshlrev_b32_e32 v16, 8, v16
	v_lshrrev_b32_e32 v22, 1, v22
	v_and_or_b32 v24, v25, 8, v24
	v_and_b32_e32 v27, 48, v21
	v_bitop3_b32 v25, v21, v26, v17 bitop3:0xde
	v_bitop3_b32 v16, v21, v16, v17 bitop3:0xde
	v_or_b32_e32 v17, v22, v20
	v_lshrrev_b32_e32 v21, 1, v24
	v_lshlrev_b32_e32 v23, 6, v23
	v_add_u32_e32 v205, 0, v16
	v_lshlrev_b32_e32 v16, 9, v17
	v_or_b32_e32 v17, v21, v20
	v_or3_b32 v16, v16, v23, v27
	v_lshlrev_b32_e32 v17, 9, v17
	v_lshlrev_b32_e32 v66, 4, v80
	v_or3_b32 v17, v17, v23, v27
	v_add_u32_e32 v206, 0, v16
	v_add_u32_e32 v204, 0, v25
	v_add_u32_e32 v207, 0, v17
	s_waitcnt vmcnt(0)
	s_mov_b64 s[2:3], 0x20000
	v_and_b32_e32 v81, 63, v80
	s_mov_b32 s12, s13
	s_mov_b32 s14, s13
	s_mov_b32 s15, s13
	s_mov_b32 s16, s13
	s_mov_b32 s17, s13
	s_mov_b32 s18, s13
	s_mov_b32 s19, s13
	s_mov_b32 s20, s13
	s_mov_b32 s21, s13
	s_mov_b32 s22, s13
	s_waitcnt vmcnt(11)
	ds_write_b128 v206, v[0:3]
	s_waitcnt vmcnt(10)
	ds_write_b128 v207, v[4:7]
	s_waitcnt vmcnt(9)
	ds_write_b128 v204, v[8:11] offset:32768
	s_waitcnt vmcnt(8)
	ds_write_b128 v205, v[12:15] offset:32768
	v_lshlrev_b32_e32 v12, 8, v155
	v_and_b32_e32 v13, 0x70, v66
	v_bitop3_b32 v0, v184, v12, v13 bitop3:0xde
	v_add_u32_e32 v183, 0, v0
	s_waitcnt lgkmcnt(0)
	s_barrier
; #define MFMA32(a, b, c) __builtin_amdgcn_mfma_f32_32x32x16_bf16((a), (b), (c), 0, 0, 0)
; DI float smA_max0(const f32x16& p0) {
;     float mx = p0[0];
; #pragma unroll
;     for (int r = 1; r < 16; ++r) mx = fmaxf(mx, p0[r]);
;     return mx;
; }
; DI float smA_max1(float mx, const f32x16& p1) {
; #pragma unroll
;     for (int r = 0; r < 16; ++r) mx = fmaxf(mx, p1[r]);
;     auto rr = __builtin_amdgcn_permlane32_swap(__float_as_uint(mx), __float_as_uint(mx), false, false);
;     return fmaxf(__uint_as_float(rr[0]), __uint_as_float(rr[1]));
; }
; template <int LO> DI void smA_exp(f32x16& p0) {
; #pragma unroll
;     for (int r = LO; r < LO + 8; ++r) p0[r] = __builtin_amdgcn_exp2f(p0[r]);
; }
; template <bool FIRST> DI void smB(f32x16& p0, f32x16& p1, float pmax, float& m_reg, float& alpha) {
;     if (!FIRST && __builtin_expect(__all(pmax <= ATHR2), 1)) { alpha = 1.f; }
;     else {
;         const float delta = FIRST ? pmax : fmaxf(pmax, 0.f);
;         alpha = __builtin_amdgcn_exp2f(-delta); m_reg += delta;
; #pragma unroll
;         for (int r = 0; r < 16; ++r) { p0[r] *= alpha; p1[r] -= delta; }
;     }
; }
; template <bool FIRST> DI void partialSM(f32x16& p0, f32x16& p1, float& m_reg, float& alpha) {
;     const float pmax = smA_max1(smA_max0(p0), p1);
;     smA_exp<0>(p0); smA_exp<8>(p0);
;     smB<FIRST>(p0, p1, pmax, m_reg, alpha);
; }
; DI void qkt(f32x16& p0, f32x16& p1, const char* Ks, const bf16x8* qr, float negm, int r32, int hi) {
; #pragma unroll
;     for (int i = 0; i < 16; ++i) { p0[i] = negm; p1[i] = negm; }
; #pragma unroll
;     for (int d0 = 0; d0 < 8; ++d0) { const int cb = (d0 * 16 + hi * 8) * 2;
;         bf16x8 b0 = *(const bf16x8*)(Ks + KSWZ(r32, cb));
;         bf16x8 b1 = *(const bf16x8*)(Ks + KSWZ(32 + r32, cb));
;         p0 = MFMA32(b0, qr[d0], p0);
;         p1 = MFMA32(b1, qr[d0], p1); }
; }
	ds_read_b128 v[0:3], v183 offset:32768
	ds_read_b128 v[4:7], v183 offset:40960
	s_waitcnt vmcnt(7) lgkmcnt(1)
	v_mfma_f32_32x32x16_bf16 v[32:47], v[0:3], v[140:143], 0
	v_or_b32_e32 v0, 32, v184
	v_bitop3_b32 v0, v0, v12, v13 bitop3:0xde
	v_add_u32_e32 v208, 0, v0
	v_lshl_add_u64 v[8:9], v[50:51], 0, s[2:3]
	v_lshl_add_u64 v[10:11], v[50:51], 0, s[56:57]
	s_add_i32 s2, 0, 0x10000
	s_cmp_lg_u32 0, -1
	s_waitcnt lgkmcnt(0)
	v_mfma_f32_32x32x16_bf16 v[16:31], v[4:7], v[140:143], 0
	ds_read_b128 v[0:3], v208 offset:32768
	ds_read_b128 v[4:7], v208 offset:40960
	s_mov_b32 s23, s13
	s_mov_b32 s24, s13
	s_mov_b32 s25, s13
	s_mov_b32 s26, s13
	s_mov_b32 s27, s13
	s_cselect_b32 s43, 0, 0
	s_waitcnt vmcnt(6) lgkmcnt(1)
	v_mfma_f32_32x32x16_bf16 v[32:47], v[0:3], v[136:139], v[32:47]
	v_or_b32_e32 v0, 64, v184
	v_bitop3_b32 v0, v0, v12, v13 bitop3:0xde
	v_add_u32_e32 v209, 0, v0
	s_mov_b32 s42, 2
	v_mov_b32_e32 v173, 0
	s_waitcnt lgkmcnt(0)
	v_mfma_f32_32x32x16_bf16 v[16:31], v[4:7], v[136:139], v[16:31]
	ds_read_b128 v[0:3], v209 offset:32768
	ds_read_b128 v[4:7], v209 offset:40960
	s_waitcnt vmcnt(5) lgkmcnt(1)
	v_mfma_f32_32x32x16_bf16 v[32:47], v[0:3], v[132:135], v[32:47]
	v_or_b32_e32 v0, 0x60, v184
	v_bitop3_b32 v0, v0, v12, v13 bitop3:0xde
	v_add_u32_e32 v210, 0, v0
	s_waitcnt lgkmcnt(0)
	v_mfma_f32_32x32x16_bf16 v[16:31], v[4:7], v[132:135], v[16:31]
	ds_read_b128 v[0:3], v210 offset:32768
	ds_read_b128 v[4:7], v210 offset:40960
	s_waitcnt vmcnt(4) lgkmcnt(1)
	v_mfma_f32_32x32x16_bf16 v[32:47], v[0:3], v[128:131], v[32:47]
	v_or_b32_e32 v0, 0x80, v184
	v_bitop3_b32 v0, v0, v12, v13 bitop3:0xde
	v_add_u32_e32 v211, 0, v0
	ds_read_b128 v[0:3], v211 offset:32768
	s_waitcnt lgkmcnt(1)
	v_mfma_f32_32x32x16_bf16 v[16:31], v[4:7], v[128:131], v[16:31]
	ds_read_b128 v[4:7], v211 offset:40960
	v_lshlrev_b32_e32 v8, 3, v81
	v_lshlrev_b32_e32 v10, 1, v80
	s_waitcnt vmcnt(7) lgkmcnt(1)
	v_mfma_f32_32x32x16_bf16 v[32:47], v[0:3], v[124:127], v[32:47]
	v_or_b32_e32 v0, 0xa0, v184
	v_bitop3_b32 v0, v0, v12, v13 bitop3:0xde
	v_add_u32_e32 v212, 0, v0
	ds_read_b128 v[0:3], v212 offset:32768
	s_waitcnt lgkmcnt(1)
	v_mfma_f32_32x32x16_bf16 v[16:31], v[4:7], v[124:127], v[16:31]
	v_and_b32_e32 v4, 0x3fffffc0, v80
	v_lshl_add_u32 v171, v4, 2, s2
	ds_read_b128 v[4:7], v212 offset:40960
	v_cmp_gt_u32_e64 s[2:3], 32, v81
	v_lshl_add_u32 v172, v155, 2, v171
	s_waitcnt vmcnt(6) lgkmcnt(1)
	v_mfma_f32_32x32x16_bf16 v[32:47], v[0:3], v[120:123], v[32:47]
	v_and_b32_e32 v0, 0xc0, v66
	v_and_or_b32 v9, v8, 24, v0
	v_or_b32_e32 v0, 0xc0, v184
	v_bitop3_b32 v0, v0, v12, v13 bitop3:0xde
	v_add_u32_e32 v213, 0, v0
	ds_read_b128 v[0:3], v213 offset:32768
	s_waitcnt lgkmcnt(1)
	v_mfma_f32_32x32x16_bf16 v[16:31], v[4:7], v[120:123], v[16:31]
	v_and_b32_e32 v4, 32, v10
	v_and_b32_e32 v5, 0x100, v8
	v_or3_b32 v82, v9, v4, v5
	ds_read_b128 v[4:7], v213 offset:40960
	v_add_u32_e32 v175, s43, v82
	s_addk_i32 s43, 0x4000
	v_add_u32_e32 v174, s43, v82
	s_waitcnt vmcnt(5) lgkmcnt(1)
	v_mfma_f32_32x32x16_bf16 v[32:47], v[0:3], v[116:119], v[32:47]
	v_or_b32_e32 v0, 0xe0, v184
	v_bitop3_b32 v0, v0, v12, v13 bitop3:0xde
	v_add_u32_e32 v214, 0, v0
	ds_read_b128 v[0:3], v214 offset:32768
	ds_read_b128 v[66:69], v214 offset:40960
	s_waitcnt vmcnt(0)
	s_waitcnt vmcnt(3)
	s_waitcnt vmcnt(2)
	s_waitcnt vmcnt(1)
	s_waitcnt vmcnt(0)
	s_waitcnt lgkmcnt(6)
	v_mfma_f32_32x32x16_bf16 v[16:31], v[4:7], v[116:119], v[16:31]
	s_waitcnt lgkmcnt(0)
	s_barrier
	v_mfma_f32_32x32x16_bf16 v[32:47], v[0:3], v[112:115], v[32:47]
	v_mov_b64_e32 v[0:1], s[12:13]
	v_mov_b64_e32 v[14:15], s[26:27]
	v_mov_b64_e32 v[2:3], s[14:15]
	v_mov_b64_e32 v[4:5], s[16:17]
	v_mov_b64_e32 v[6:7], s[18:19]
	v_mov_b64_e32 v[8:9], s[20:21]
	v_mov_b64_e32 v[10:11], s[22:23]
	v_mfma_f32_32x32x16_bf16 v[16:31], v[66:69], v[112:115], v[16:31]
	s_nop 3
	v_max_f32_e32 v66, v33, v33
	v_max_f32_e32 v67, v32, v32
	v_max_f32_e32 v66, v67, v66
	v_max3_f32 v66, v66, v34, v35
	v_max3_f32 v66, v66, v36, v37
	v_max3_f32 v66, v66, v38, v39
	v_max3_f32 v66, v66, v40, v41
	v_max3_f32 v66, v66, v42, v43
	v_max3_f32 v66, v66, v44, v45
	v_max3_f32 v66, v66, v46, v47
	v_max3_f32 v66, v66, v16, v17
	v_max3_f32 v66, v66, v18, v19
	v_max3_f32 v66, v66, v20, v21
	v_max3_f32 v66, v66, v22, v23
	v_max3_f32 v66, v66, v24, v25
	v_max3_f32 v66, v66, v26, v27
	v_max3_f32 v66, v66, v28, v29
	v_max3_f32 v66, v66, v30, v31
	v_mov_b32_e32 v67, v66
	s_nop 1
	v_permlane32_swap_b32_e32 v66, v67
	v_max_f32_e32 v50, v67, v67
	v_max_f32_e32 v51, v66, v66
	v_max_f32_e32 v50, v51, v50
	v_exp_f32_e32 v32, v32
	v_exp_f32_e64 v150, -v50
	v_exp_f32_e32 v33, v33
	v_exp_f32_e32 v34, v34
	v_exp_f32_e32 v35, v35
	v_exp_f32_e32 v36, v36
	v_exp_f32_e32 v37, v37
	v_exp_f32_e32 v38, v38
	v_exp_f32_e32 v39, v39
	v_exp_f32_e32 v40, v40
	v_exp_f32_e32 v42, v42
	v_exp_f32_e32 v44, v44
	v_exp_f32_e32 v46, v46
	v_exp_f32_e32 v47, v47
	v_exp_f32_e32 v45, v45
	v_exp_f32_e32 v43, v43
	v_exp_f32_e32 v41, v41
	v_sub_f32_e32 v66, v18, v50
	v_sub_f32_e32 v65, v17, v50
	v_sub_f32_e32 v64, v16, v50
	v_lshl_add_u64 v[16:17], s[68:69], 0, v[48:49]
	v_and_b32_e32 v18, 15, v80
	v_lshlrev_b64 v[16:17], 11, v[16:17]
	v_lshlrev_b32_e32 v18, 4, v18
	v_or3_b32 v16, v16, s72, v18
	v_mov_b64_e32 v[12:13], s[24:25]
	v_pk_mul_f32 v[146:147], v[46:47], v[150:151] op_sel_hi:[1,0]
	v_pk_mul_f32 v[160:161], v[44:45], v[150:151] op_sel_hi:[1,0]
	v_pk_mul_f32 v[164:165], v[42:43], v[150:151] op_sel_hi:[1,0]
	v_pk_mul_f32 v[168:169], v[40:41], v[150:151] op_sel_hi:[1,0]
	v_pk_mul_f32 v[156:157], v[38:39], v[150:151] op_sel_hi:[1,0]
	v_pk_mul_f32 v[158:159], v[36:37], v[150:151] op_sel_hi:[1,0]
	v_pk_mul_f32 v[162:163], v[34:35], v[150:151] op_sel_hi:[1,0]
	v_pk_mul_f32 v[166:167], v[32:33], v[150:151] op_sel_hi:[1,0]
	v_sub_f32_e32 v79, v31, v50
	v_sub_f32_e32 v78, v30, v50
	v_sub_f32_e32 v77, v29, v50
	v_sub_f32_e32 v76, v28, v50
	v_sub_f32_e32 v75, v27, v50
	v_sub_f32_e32 v74, v26, v50
	v_sub_f32_e32 v73, v25, v50
	v_sub_f32_e32 v72, v24, v50
	v_sub_f32_e32 v71, v23, v50
	v_sub_f32_e32 v70, v22, v50
	v_sub_f32_e32 v69, v21, v50
	v_sub_f32_e32 v68, v20, v50
	v_sub_f32_e32 v67, v19, v50
	v_add_f32_e32 v215, 0, v50
	v_lshl_add_u64 v[152:153], s[40:41], 0, v[16:17]
	v_mov_b64_e32 v[62:63], v[14:15]
	v_mov_b64_e32 v[30:31], v[14:15]
	v_mov_b64_e32 v[46:47], v[14:15]
	v_mov_b64_e32 v[60:61], v[12:13]
	v_mov_b64_e32 v[58:59], v[10:11]
	v_mov_b64_e32 v[56:57], v[8:9]
	v_mov_b64_e32 v[54:55], v[6:7]
	v_mov_b64_e32 v[52:53], v[4:5]
	v_mov_b64_e32 v[50:51], v[2:3]
	v_mov_b64_e32 v[48:49], v[0:1]
	v_mov_b64_e32 v[28:29], v[12:13]
	v_mov_b64_e32 v[26:27], v[10:11]
	v_mov_b64_e32 v[24:25], v[8:9]
	v_mov_b64_e32 v[22:23], v[6:7]
	v_mov_b64_e32 v[20:21], v[4:5]
	v_mov_b64_e32 v[18:19], v[2:3]
	v_mov_b64_e32 v[16:17], v[0:1]
	v_mov_b64_e32 v[44:45], v[12:13]
	v_mov_b64_e32 v[42:43], v[10:11]
	v_mov_b64_e32 v[40:41], v[8:9]
	v_mov_b64_e32 v[38:39], v[6:7]
	v_mov_b64_e32 v[36:37], v[4:5]
	v_mov_b64_e32 v[34:35], v[2:3]
	v_mov_b64_e32 v[32:33], v[0:1]
	.p2align 6
; #define SBAR() __builtin_amdgcn_sched_barrier(0)
; DI void finishSM(f32x16& p0, f32x16& p1, float alpha, float& l_reg, bf16x8& pa0, bf16x8& pa1, bf16x8& pa2, bf16x8& pa3) {
; #pragma unroll
;     for (int r = 0; r < 16; ++r) p1[r] = __builtin_amdgcn_exp2f(p1[r]);
;     float ps = 0;
; #pragma unroll
;     for (int r = 0; r < 16; ++r) ps += p0[r];
; #pragma unroll
;     for (int r = 0; r < 16; ++r) ps += p1[r];
;     { auto rr = __builtin_amdgcn_permlane32_swap(__float_as_uint(ps), __float_as_uint(ps), false, false);
;       ps = __uint_as_float(rr[0]) + __uint_as_float(rr[1]); }
;     l_reg = l_reg * alpha + ps;
; DI void attn_unit(const bf16_t* __restrict__ Qb, const bf16_t* __restrict__ Kh, const bf16_t* __restrict__ Vh, bf16_t* __restrict__ Ob, const float* __restrict__ onw, int seq, char* lds) {
;     ...
;     for (int j = 1; j + 1 < NT; j += 2) {
;         SBAR(); qkt(pB0, pB1, K_lds + SHM_K, qr, -m_reg, r32, hi);
;         finishSM(pA0, pA1, alA, l_reg, pa0, pa1, pa2, pa3); SBAR();
.LBB0_580:
	s_add_u32 m0, s100, 0x8000
	s_nop 0
	global_load_lds_dwordx4 v246, s[98:99]
	s_add_u32 m0, s100, 0xa000
	s_nop 0
	global_load_lds_dwordx4 v247, s[98:99]
	s_add_u32 m0, s100, 0x4000
	s_nop 0
	global_load_lds_dwordx4 v248, s[98:99]
	s_add_u32 m0, s100, 0x6000
	s_nop 0
	global_load_lds_dwordx4 v249, s[98:99]
	s_add_u32 s98, s98, 0x20000
	s_addc_u32 s99, s99, 0
	ds_read_b128 v[216:219], v183 offset:49152
	ds_read_b128 v[220:223], v183 offset:57344
	v_xor_b32_e32 v80, 0x80000000, v215
	v_mov_b32_e32 v81, v80
	v_mov_b32_e32 v82, v80
	v_mov_b32_e32 v83, v80
	v_mov_b32_e32 v84, v80
	v_mov_b32_e32 v85, v80
	v_mov_b32_e32 v86, v80
	v_mov_b32_e32 v87, v80
	v_mov_b32_e32 v88, v80
	v_mov_b32_e32 v89, v80
	v_mov_b32_e32 v90, v80
	v_mov_b32_e32 v91, v80
	v_mov_b32_e32 v92, v80
	v_mov_b32_e32 v93, v80
	v_mov_b32_e32 v94, v80
	v_mov_b32_e32 v95, v80
	v_add_f32_e32 v144, 0, v166
	v_add_f32_e32 v144, v167, v144
	s_waitcnt lgkmcnt(1)
	v_mfma_f32_32x32x16_bf16 v[96:111], v[216:219], v[140:143], v[80:95]
	v_add_f32_e32 v144, v162, v144
	v_add_f32_e32 v144, v163, v144
	v_add_f32_e32 v144, v158, v144
	v_add_f32_e32 v144, v159, v144
	v_add_f32_e32 v144, v156, v144
	v_add_f32_e32 v144, v157, v144
	v_add_f32_e32 v144, v168, v144
	s_waitcnt lgkmcnt(0)
	v_mfma_f32_32x32x16_bf16 v[80:95], v[220:223], v[140:143], v[80:95]
	ds_read_b128 v[216:219], v208 offset:49152
	ds_read_b128 v[220:223], v208 offset:57344
	v_add_f32_e32 v144, v169, v144
	v_add_f32_e32 v144, v164, v144
	v_add_f32_e32 v144, v165, v144
	v_exp_f32_e32 v64, v64
	v_add_f32_e32 v144, v160, v144
	v_exp_f32_e32 v65, v65
	s_waitcnt lgkmcnt(0)
	v_mfma_f32_32x32x16_bf16 v[80:95], v[220:223], v[136:139], v[80:95]
	v_add_f32_e32 v144, v161, v144
	v_exp_f32_e32 v66, v66
	v_add_f32_e32 v144, v146, v144
	v_exp_f32_e32 v67, v67
	v_add_f32_e32 v144, v147, v144
	v_exp_f32_e32 v68, v68
	v_add_f32_e32 v144, v64, v144
	v_mfma_f32_32x32x16_bf16 v[96:111], v[216:219], v[136:139], v[96:111]
	ds_read_b128 v[216:219], v209 offset:49152
	ds_read_b128 v[220:223], v209 offset:57344
	v_exp_f32_e32 v69, v69
	v_add_f32_e32 v144, v65, v144
	v_exp_f32_e32 v70, v70
	v_add_f32_e32 v144, v66, v144
	v_exp_f32_e32 v71, v71
	v_add_f32_e32 v144, v67, v144
	s_waitcnt lgkmcnt(0)
	v_mfma_f32_32x32x16_bf16 v[80:95], v[220:223], v[132:135], v[80:95]
	v_exp_f32_e32 v72, v72
	v_add_f32_e32 v144, v68, v144
	v_exp_f32_e32 v73, v73
	v_add_f32_e32 v144, v69, v144
	v_exp_f32_e32 v74, v74
	v_add_f32_e32 v144, v70, v144
	v_exp_f32_e32 v75, v75
	v_mfma_f32_32x32x16_bf16 v[96:111], v[216:219], v[132:135], v[96:111]
	ds_read_b128 v[216:219], v210 offset:49152
	ds_read_b128 v[220:223], v210 offset:57344
	v_add_f32_e32 v144, v71, v144
	v_exp_f32_e32 v76, v76
	v_add_f32_e32 v144, v72, v144
	v_exp_f32_e32 v77, v77
	v_add_f32_e32 v144, v73, v144
	v_exp_f32_e32 v78, v78
	s_waitcnt lgkmcnt(0)
	v_mfma_f32_32x32x16_bf16 v[80:95], v[220:223], v[128:131], v[80:95]
	v_add_f32_e32 v144, v74, v144
	v_exp_f32_e32 v79, v79
	v_add_f32_e32 v144, v75, v144
	v_add_f32_e32 v144, v76, v144
	v_add_f32_e32 v144, v77, v144
	v_add_f32_e32 v144, v78, v144
	v_mfma_f32_32x32x16_bf16 v[96:111], v[216:219], v[128:131], v[96:111]
	ds_read_b128 v[216:219], v211 offset:49152
	ds_read_b128 v[220:223], v211 offset:57344
	s_waitcnt lgkmcnt(0)
	v_mfma_f32_32x32x16_bf16 v[80:95], v[220:223], v[124:127], v[80:95]
	v_mfma_f32_32x32x16_bf16 v[96:111], v[216:219], v[124:127], v[96:111]
	ds_read_b128 v[216:219], v212 offset:49152
	ds_read_b128 v[220:223], v212 offset:57344
	s_waitcnt lgkmcnt(0)
	v_mfma_f32_32x32x16_bf16 v[80:95], v[220:223], v[120:123], v[80:95]
	v_mfma_f32_32x32x16_bf16 v[96:111], v[216:219], v[120:123], v[96:111]
	ds_read_b128 v[216:219], v213 offset:49152
	ds_read_b128 v[220:223], v213 offset:57344
	s_waitcnt lgkmcnt(0)
	v_mfma_f32_32x32x16_bf16 v[80:95], v[220:223], v[116:119], v[80:95]
	v_mfma_f32_32x32x16_bf16 v[96:111], v[216:219], v[116:119], v[96:111]
	ds_read_b128 v[216:219], v214 offset:49152
	ds_read_b128 v[220:223], v214 offset:57344
	s_waitcnt lgkmcnt(0)
; DI void finishSM(f32x16& p0, f32x16& p1, float alpha, float& l_reg, bf16x8& pa0, bf16x8& pa1, bf16x8& pa2, bf16x8& pa3) {
; #pragma unroll
;     for (int r = 0; r < 16; ++r) p1[r] = __builtin_amdgcn_exp2f(p1[r]);
;     float ps = 0;
; #pragma unroll
;     for (int r = 0; r < 16; ++r) ps += p0[r];
; #pragma unroll
;     for (int r = 0; r < 16; ++r) ps += p1[r];
;     { auto rr = __builtin_amdgcn_permlane32_swap(__float_as_uint(ps), __float_as_uint(ps), false, false);
;       ps = __uint_as_float(rr[0]) + __uint_as_float(rr[1]); }
;     l_reg = l_reg * alpha + ps;
;     ...
;     PK4(p0, 0, pa0); PK4(p0, 8, pa1); PK4(p1, 0, pa2); PK4(p1, 8, pa3);
;     ...
; }
; DI void qkt(f32x16& p0, f32x16& p1, const char* Ks, const bf16x8* qr, float negm, int r32, int hi) {
; #pragma unroll
;     for (int i = 0; i < 16; ++i) { p0[i] = negm; p1[i] = negm; }
; #pragma unroll
;     for (int d0 = 0; d0 < 8; ++d0) { const int cb = (d0 * 16 + hi * 8) * 2;
;         bf16x8 b0 = *(const bf16x8*)(Ks + KSWZ(r32, cb));
;         bf16x8 b1 = *(const bf16x8*)(Ks + KSWZ(32 + r32, cb));
;         p0 = MFMA32(b0, qr[d0], p0);
;         p1 = MFMA32(b1, qr[d0], p1); }
; }
; DI int v_st(int k, int c) { const int kk = (k & ~0xC) | ((k & 4) << 1) | ((k & 8) >> 1); return ((kk >> 3) * 4 + (c >> 5)) * 512 + ((kk & 7) * 32 + (c & 31)) * 2; }
; DI int v_rd_base(int lane) { return ((lane & 3) << 3) | (((lane >> 2) & 3) << 6) | (((lane >> 4) & 1) << 5) | (((lane >> 5) & 1) << 8); }
; template <int OFF> DI s16x4 tr_read(int vb) { s16x4 r; asm volatile("ds_read_b64_tr_b16 %0, %1 offset:%2" : "=&v"(r) : "v"(vb), "i"(OFF) : "memory"); return r; }
; template <int D0> DI void pv_one(f32x16& od, int vb, bf16x8 pa0, bf16x8 pa1, bf16x8 pa2, bf16x8 pa3) {
;     const s16x4 l0 = tr_read<v_rd_off(D0, 0, 0)>(vb), h0 = tr_read<v_rd_off(D0, 0, 1)>(vb), l1 = tr_read<v_rd_off(D0, 1, 0)>(vb), h1 = tr_read<v_rd_off(D0, 1, 1)>(vb);
;     const s16x4 l2 = tr_read<v_rd_off(D0, 2, 0)>(vb), h2 = tr_read<v_rd_off(D0, 2, 1)>(vb), l3 = tr_read<v_rd_off(D0, 3, 0)>(vb), h3 = tr_read<v_rd_off(D0, 3, 1)>(vb);
;     asm volatile("s_waitcnt lgkmcnt(0)" ::: "memory"); SBAR();
;     ...
;     od = MFMA32(pa0, PK(l0, h0), od);
;     od = MFMA32(pa1, PK(l1, h1), od);
;     od = MFMA32(pa2, PK(l2, h2), od);
;     od = MFMA32(pa3, PK(l3, h3), od);
;     ...
; }
; DI float pv_d0_sm(f32x16* o, int vb, bf16x8 pa0, bf16x8 pa1, bf16x8 pa2, bf16x8 pa3, f32x16& q0, f32x16& q1) {
	v_mfma_f32_32x32x16_bf16 v[80:95], v[220:223], v[112:115], v[80:95]
	v_mfma_f32_32x32x16_bf16 v[96:111], v[216:219], v[112:115], v[96:111]
	v_add_f32_e32 v216, v79, v144
	v_mov_b32_e32 v217, v216
	v_cvt_pk_bf16_f32 v218, v166, v167
	v_cvt_pk_bf16_f32 v219, v162, v163
	v_cvt_pk_bf16_f32 v220, v158, v159
	v_cvt_pk_bf16_f32 v221, v156, v157
	v_cvt_pk_bf16_f32 v162, v168, v169
	v_cvt_pk_bf16_f32 v163, v164, v165
	v_cvt_pk_bf16_f32 v164, v160, v161
	v_cvt_pk_bf16_f32 v165, v146, v147
	s_nop 1
	v_permlane32_swap_b32_e32 v216, v217
	v_permlane32_swap_b32_e32 v162, v164
	v_permlane32_swap_b32_e32 v163, v165
	v_cvt_pk_bf16_f32 v222, v64, v65
	v_cvt_pk_bf16_f32 v223, v66, v67
	v_cvt_pk_bf16_f32 v224, v68, v69
	v_cvt_pk_bf16_f32 v225, v70, v71
	v_cvt_pk_bf16_f32 v226, v72, v73
	v_cvt_pk_bf16_f32 v227, v74, v75
	v_cvt_pk_bf16_f32 v228, v76, v77
	v_cvt_pk_bf16_f32 v229, v78, v79
	v_permlane32_swap_b32_e32 v218, v220
	v_permlane32_swap_b32_e32 v219, v221
	v_permlane32_swap_b32_e32 v222, v224
	v_permlane32_swap_b32_e32 v223, v225
	v_permlane32_swap_b32_e32 v226, v228
	v_permlane32_swap_b32_e32 v227, v229
	ds_read_b64_tr_b16 v[144:145], v175 offset:0
	ds_read_b64_tr_b16 v[146:147], v175 offset:0x800
	ds_read_b64_tr_b16 v[156:157], v175 offset:0x1000
	ds_read_b64_tr_b16 v[158:159], v175 offset:0x1800
	ds_read_b64_tr_b16 v[166:167], v175 offset:0x2000
	ds_read_b64_tr_b16 v[168:169], v175 offset:0x2800
	ds_read_b64_tr_b16 v[230:231], v175 offset:0x3000
	ds_read_b64_tr_b16 v[232:233], v175 offset:0x3800
	s_waitcnt lgkmcnt(0)
	s_nop 0
	v_mfma_f32_32x32x16_bf16 v[0:15], v[218:221], v[144:147], v[0:15]
	v_max_f32_e32 v144, v97, v97
	v_max_f32_e32 v145, v96, v96
	v_max_f32_e32 v144, v145, v144
	v_max3_f32 v144, v144, v98, v99
	v_max3_f32 v144, v144, v100, v101
	v_max3_f32 v144, v144, v102, v103
	v_max3_f32 v144, v144, v104, v105
	v_mfma_f32_32x32x16_bf16 v[0:15], v[162:165], v[156:159], v[0:15]
	v_max3_f32 v144, v144, v106, v107
	v_max3_f32 v146, v144, v108, v109
	ds_read_b64_tr_b16 v[144:145], v175 offset:0x200
	v_max3_f32 v154, v146, v110, v111
	ds_read_b64_tr_b16 v[146:147], v175 offset:0xa00
	ds_read_b64_tr_b16 v[156:157], v175 offset:0x1200
	ds_read_b64_tr_b16 v[158:159], v175 offset:0x1a00
	v_mfma_f32_32x32x16_bf16 v[0:15], v[222:225], v[166:169], v[0:15]
	ds_read_b64_tr_b16 v[234:235], v175 offset:0x2200
	ds_read_b64_tr_b16 v[236:237], v175 offset:0x2a00
	ds_read_b64_tr_b16 v[238:239], v175 offset:0x3200
	ds_read_b64_tr_b16 v[240:241], v175 offset:0x3a00
	s_waitcnt lgkmcnt(0)
	v_mfma_f32_32x32x16_bf16 v[0:15], v[226:229], v[230:233], v[0:15]
	v_mfma_f32_32x32x16_bf16 v[48:63], v[218:221], v[144:147], v[48:63]
	v_max3_f32 v154, v154, v80, v81
	v_max3_f32 v144, v154, v82, v83
	v_max3_f32 v144, v144, v84, v85
	v_max3_f32 v144, v144, v86, v87
	v_max3_f32 v144, v144, v88, v89
	v_max3_f32 v144, v144, v90, v91
	v_max3_f32 v144, v144, v92, v93
	v_mfma_f32_32x32x16_bf16 v[48:63], v[162:165], v[156:159], v[48:63]
	v_max3_f32 v144, v144, v94, v95
	v_mov_b32_e32 v145, v144
	s_nop 1
	v_permlane32_swap_b32_e32 v144, v145
	v_max_f32_e32 v145, v145, v145
	v_max_f32_e32 v144, v144, v144
	v_max_f32_e32 v168, v144, v145
	v_mfma_f32_32x32x16_bf16 v[48:63], v[222:225], v[234:237], v[48:63]
	ds_read_b64_tr_b16 v[144:145], v175 offset:0x400
	ds_read_b64_tr_b16 v[146:147], v175 offset:0xc00
	ds_read_b64_tr_b16 v[156:157], v175 offset:0x1400
	ds_read_b64_tr_b16 v[158:159], v175 offset:0x1c00
	ds_read_b64_tr_b16 v[230:231], v175 offset:0x2400
	ds_read_b64_tr_b16 v[232:233], v175 offset:0x2c00
	ds_read_b64_tr_b16 v[234:235], v175 offset:0x3400
	v_mfma_f32_32x32x16_bf16 v[48:63], v[226:229], v[238:241], v[48:63]
	ds_read_b64_tr_b16 v[236:237], v175 offset:0x3c00
	s_waitcnt lgkmcnt(0)
	v_mfma_f32_32x32x16_bf16 v[16:31], v[218:221], v[144:147], v[16:31]
	v_exp_f32_e32 v144, v96
	v_exp_f32_e32 v145, v97
	ds_read_b64_tr_b16 v[96:97], v175 offset:0x600
	v_exp_f32_e32 v146, v100
	v_exp_f32_e32 v147, v101
	v_mfma_f32_32x32x16_bf16 v[16:31], v[162:165], v[156:159], v[16:31]
	v_exp_f32_e32 v158, v98
	v_exp_f32_e32 v159, v99
	ds_read_b64_tr_b16 v[98:99], v175 offset:0xe00
	ds_read_b64_tr_b16 v[100:101], v175 offset:0x1600
	v_exp_f32_e32 v156, v102
	v_exp_f32_e32 v157, v103
	ds_read_b64_tr_b16 v[102:103], v175 offset:0x1e00
	v_mfma_f32_32x32x16_bf16 v[16:31], v[222:225], v[230:233], v[16:31]
	ds_read_b64_tr_b16 v[230:231], v175 offset:0x2600
	ds_read_b64_tr_b16 v[232:233], v175 offset:0x2e00
	ds_read_b64_tr_b16 v[238:239], v175 offset:0x3600
	ds_read_b64_tr_b16 v[240:241], v175 offset:0x3e00
	s_waitcnt lgkmcnt(0)
	v_mfma_f32_32x32x16_bf16 v[16:31], v[226:229], v[234:237], v[16:31]
	v_mfma_f32_32x32x16_bf16 v[32:47], v[218:221], v[96:99], v[32:47]
	v_exp_f32_e32 v166, v104
	v_exp_f32_e32 v167, v105
	v_exp_f32_e32 v160, v110
	v_exp_f32_e32 v161, v111
	v_cmp_ge_f32_e32 vcc, s82, v168
	v_mov_b32_e32 v154, 1.0
	s_cmp_eq_u64 vcc, exec
	v_mfma_f32_32x32x16_bf16 v[32:47], v[162:165], v[100:103], v[32:47]
	v_exp_f32_e32 v162, v106
	v_exp_f32_e32 v163, v107
	v_exp_f32_e32 v164, v108
	v_exp_f32_e32 v165, v109
	v_mfma_f32_32x32x16_bf16 v[32:47], v[222:225], v[230:233], v[32:47]
	v_mfma_f32_32x32x16_bf16 v[32:47], v[226:229], v[238:241], v[32:47]
	s_cbranch_scc0 .LBB0_593
	.p2align 6

; #define MFMA32(a, b, c) __builtin_amdgcn_mfma_f32_32x32x16_bf16((a), (b), (c), 0, 0, 0)
; #define SBAR() __builtin_amdgcn_sched_barrier(0)
; #define SLOAD(i, k0) do { sr_[i].vs0 = *(const bf16x8*)(&Vh[(long)((k0) + sr) * LDA_ + sc]); sr_[i].vs1 = *(const bf16x8*)(&Vh[(long)((k0) + 32 + sr) * LDA_ + sc]); \
;     sr_[i].ks0 = *(const bf16x8*)(&Kh[(long)((k0) + sr) * LDA_ + sc]); sr_[i].ks1 = *(const bf16x8*)(&Kh[(long)((k0) + 32 + sr) * LDA_ + sc]); } while (0)
; DI void finishSM(f32x16& p0, f32x16& p1, float alpha, float& l_reg, bf16x8& pa0, bf16x8& pa1, bf16x8& pa2, bf16x8& pa3) {
; #pragma unroll
;     for (int r = 0; r < 16; ++r) p1[r] = __builtin_amdgcn_exp2f(p1[r]);
;     float ps = 0;
; #pragma unroll
;     for (int r = 0; r < 16; ++r) ps += p0[r];
; #pragma unroll
;     for (int r = 0; r < 16; ++r) ps += p1[r];
;     { auto rr = __builtin_amdgcn_permlane32_swap(__float_as_uint(ps), __float_as_uint(ps), false, false);
;       ps = __uint_as_float(rr[0]) + __uint_as_float(rr[1]); }
;     l_reg = l_reg * alpha + ps;
;     ...
;     PK4(p0, 0, pa0); PK4(p0, 8, pa1); PK4(p1, 0, pa2); PK4(p1, 8, pa3);
;     ...
; }
; DI void qkt(f32x16& p0, f32x16& p1, const char* Ks, const bf16x8* qr, float negm, int r32, int hi) {
; #pragma unroll
;     for (int i = 0; i < 16; ++i) { p0[i] = negm; p1[i] = negm; }
; #pragma unroll
;     for (int d0 = 0; d0 < 8; ++d0) { const int cb = (d0 * 16 + hi * 8) * 2;
;         bf16x8 b0 = *(const bf16x8*)(Ks + KSWZ(r32, cb));
;         bf16x8 b1 = *(const bf16x8*)(Ks + KSWZ(32 + r32, cb));
;         p0 = MFMA32(b0, qr[d0], p0);
;         p1 = MFMA32(b1, qr[d0], p1); }
; }
; DI void attn_unit(const bf16_t* __restrict__ Qb, const bf16_t* __restrict__ Kh, const bf16_t* __restrict__ Vh, bf16_t* __restrict__ Ob, const float* __restrict__ onw, int seq, char* lds) {
;     ...
;         SBAR(); qkt(pB0, pB1, K_lds + SHM_K, qr, -m_reg, r32, hi);
;         finishSM(pA0, pA1, alA, l_reg, pa0, pa1, pa2, pa3); SBAR();
;         SLOAD(SO, (j + 1) * 64); SBAR();
.LBB0_595:
	s_add_u32 m0, s100, 0x4000
	s_nop 0
	global_load_lds_dwordx4 v248, s[98:99]
	s_add_u32 m0, s100, 0x6000
	s_nop 0
	global_load_lds_dwordx4 v249, s[98:99]
	ds_read_b128 v[204:207], v183 offset:49152
	ds_read_b128 v[216:219], v183 offset:57344
	v_xor_b32_e32 v80, 0x80000000, v215
	v_mov_b32_e32 v81, v80
	v_mov_b32_e32 v82, v80
	v_mov_b32_e32 v83, v80
	v_mov_b32_e32 v84, v80
	v_mov_b32_e32 v85, v80
	v_mov_b32_e32 v86, v80
	v_mov_b32_e32 v87, v80
	v_mov_b32_e32 v88, v80
	v_mov_b32_e32 v89, v80
	v_mov_b32_e32 v90, v80
	v_mov_b32_e32 v91, v80
	v_mov_b32_e32 v92, v80
	v_mov_b32_e32 v93, v80
	v_mov_b32_e32 v94, v80
	v_mov_b32_e32 v95, v80
	v_exp_f32_e32 v145, v65
	v_add_f32_e32 v65, 0, v166
	s_waitcnt lgkmcnt(1)
	v_mfma_f32_32x32x16_bf16 v[96:111], v[204:207], v[140:143], v[80:95]
	v_add_f32_e32 v65, v167, v65
	v_add_f32_e32 v65, v162, v65
	v_add_f32_e32 v65, v163, v65
	v_add_f32_e32 v65, v158, v65
	v_add_f32_e32 v65, v159, v65
	v_add_f32_e32 v65, v156, v65
	v_add_f32_e32 v65, v157, v65
	s_waitcnt lgkmcnt(0)
	v_mfma_f32_32x32x16_bf16 v[80:95], v[216:219], v[140:143], v[80:95]
	ds_read_b128 v[140:143], v208 offset:49152
	ds_read_b128 v[204:207], v208 offset:57344
	v_add_f32_e32 v65, v168, v65
	v_add_f32_e32 v65, v169, v65
	v_add_f32_e32 v65, v164, v65
	v_add_f32_e32 v65, v165, v65
	v_exp_f32_e32 v64, v64
	v_add_f32_e32 v65, v160, v65
	s_waitcnt lgkmcnt(1)
	v_mfma_f32_32x32x16_bf16 v[96:111], v[140:143], v[136:139], v[96:111]
	ds_read_b128 v[140:143], v209 offset:49152
	ds_read_b128 v[216:219], v209 offset:57344
	v_add_f32_e32 v65, v161, v65
	v_exp_f32_e32 v66, v66
	v_add_f32_e32 v65, v146, v65
	v_exp_f32_e32 v67, v67
	v_add_f32_e32 v65, v147, v65
	v_exp_f32_e32 v68, v68
	s_waitcnt lgkmcnt(2)
	v_mfma_f32_32x32x16_bf16 v[80:95], v[204:207], v[136:139], v[80:95]
	ds_read_b128 v[136:139], v210 offset:49152
	ds_read_b128 v[204:207], v210 offset:57344
	ds_read_b128 v[220:223], v211 offset:49152
	ds_read_b128 v[208:211], v211 offset:57344
	ds_read_b128 v[224:227], v212 offset:49152
	ds_read_b128 v[228:231], v212 offset:57344
	ds_read_b128 v[232:235], v213 offset:49152
	ds_read_b128 v[236:239], v213 offset:57344
	v_add_f32_e32 v65, v64, v65
	v_exp_f32_e32 v69, v69
	v_add_f32_e32 v65, v145, v65
	v_exp_f32_e32 v70, v70
	v_add_f32_e32 v65, v66, v65
	v_exp_f32_e32 v71, v71
	s_waitcnt lgkmcnt(9)
	v_mfma_f32_32x32x16_bf16 v[96:111], v[140:143], v[132:135], v[96:111]
	v_add_f32_e32 v65, v67, v65
	v_exp_f32_e32 v72, v72
	v_add_f32_e32 v65, v68, v65
	ds_read_b128 v[140:143], v214 offset:49152
	ds_read_b128 v[212:215], v214 offset:57344
	v_exp_f32_e32 v73, v73
	v_add_f32_e32 v65, v69, v65
	v_add_f32_e32 v65, v70, v65
	s_waitcnt lgkmcnt(10)
	v_mfma_f32_32x32x16_bf16 v[80:95], v[216:219], v[132:135], v[80:95]
	v_exp_f32_e32 v132, v74
	v_exp_f32_e32 v133, v75
	v_add_f32_e32 v65, v71, v65
	v_exp_f32_e32 v134, v76
	v_add_f32_e32 v65, v72, v65
	v_exp_f32_e32 v135, v77
	v_add_f32_e32 v65, v73, v65
	s_waitcnt lgkmcnt(9)
	v_mfma_f32_32x32x16_bf16 v[96:111], v[136:139], v[128:131], v[96:111]
	v_exp_f32_e32 v78, v78
	v_add_f32_e32 v65, v132, v65
	v_exp_f32_e32 v79, v79
	v_add_f32_e32 v65, v133, v65
	v_add_f32_e32 v65, v134, v65
	v_add_f32_e32 v65, v135, v65
	v_add_f32_e32 v65, v78, v65
	s_waitcnt lgkmcnt(8)
	v_mfma_f32_32x32x16_bf16 v[80:95], v[204:207], v[128:131], v[80:95]
	v_add_f32_e32 v65, v79, v65
	v_cvt_pk_bf16_f32 v74, v166, v167
	v_cvt_pk_bf16_f32 v75, v162, v163
	v_cvt_pk_bf16_f32 v76, v158, v159
	v_cvt_pk_bf16_f32 v77, v156, v157
	s_nop 0
	v_permlane32_swap_b32_e32 v74, v76
	s_waitcnt lgkmcnt(7)
	v_mfma_f32_32x32x16_bf16 v[96:111], v[220:223], v[124:127], v[96:111]
	v_permlane32_swap_b32_e32 v75, v77
	s_waitcnt lgkmcnt(6)
	v_mfma_f32_32x32x16_bf16 v[80:95], v[208:211], v[124:127], v[80:95]
	s_waitcnt lgkmcnt(5)
	v_mfma_f32_32x32x16_bf16 v[96:111], v[224:227], v[120:123], v[96:111]
	s_waitcnt lgkmcnt(4)
	v_mfma_f32_32x32x16_bf16 v[80:95], v[228:231], v[120:123], v[80:95]
	v_mov_b32_e32 v120, v65
	s_nop 1
	v_permlane32_swap_b32_e32 v65, v120
	v_cvt_pk_bf16_f32 v122, v168, v169
	v_cvt_pk_bf16_f32 v123, v164, v165
	v_cvt_pk_bf16_f32 v124, v160, v161
	v_cvt_pk_bf16_f32 v125, v146, v147
	s_waitcnt lgkmcnt(3)
	v_mfma_f32_32x32x16_bf16 v[96:111], v[232:235], v[116:119], v[96:111]
	v_permlane32_swap_b32_e32 v122, v124
	v_permlane32_swap_b32_e32 v123, v125
	s_waitcnt lgkmcnt(2)
	v_mfma_f32_32x32x16_bf16 v[80:95], v[236:239], v[116:119], v[80:95]
	v_cvt_pk_bf16_f32 v116, v64, v145
	v_cvt_pk_bf16_f32 v117, v66, v67
	v_cvt_pk_bf16_f32 v118, v68, v69
	v_cvt_pk_bf16_f32 v119, v70, v71
	v_cvt_pk_bf16_f32 v126, v72, v73
	v_cvt_pk_bf16_f32 v127, v132, v133
	v_cvt_pk_bf16_f32 v128, v134, v135
	s_waitcnt lgkmcnt(1)
; DI void finishSM(f32x16& p0, f32x16& p1, float alpha, float& l_reg, bf16x8& pa0, bf16x8& pa1, bf16x8& pa2, bf16x8& pa3) {
; #pragma unroll
;     for (int r = 0; r < 16; ++r) p1[r] = __builtin_amdgcn_exp2f(p1[r]);
;     float ps = 0;
; #pragma unroll
;     for (int r = 0; r < 16; ++r) ps += p0[r];
; #pragma unroll
;     for (int r = 0; r < 16; ++r) ps += p1[r];
;     { auto rr = __builtin_amdgcn_permlane32_swap(__float_as_uint(ps), __float_as_uint(ps), false, false);
;       ps = __uint_as_float(rr[0]) + __uint_as_float(rr[1]); }
;     l_reg = l_reg * alpha + ps;
;     ...
;     PK4(p0, 0, pa0); PK4(p0, 8, pa1); PK4(p1, 0, pa2); PK4(p1, 8, pa3);
;     ...
; }
; DI void qkt(f32x16& p0, f32x16& p1, const char* Ks, const bf16x8* qr, float negm, int r32, int hi) {
; #pragma unroll
;     for (int i = 0; i < 16; ++i) { p0[i] = negm; p1[i] = negm; }
; #pragma unroll
;     for (int d0 = 0; d0 < 8; ++d0) { const int cb = (d0 * 16 + hi * 8) * 2;
;         bf16x8 b0 = *(const bf16x8*)(Ks + KSWZ(r32, cb));
;         bf16x8 b1 = *(const bf16x8*)(Ks + KSWZ(32 + r32, cb));
;         p0 = MFMA32(b0, qr[d0], p0);
;         p1 = MFMA32(b1, qr[d0], p1); }
; }
; DI int v_st(int k, int c) { const int kk = (k & ~0xC) | ((k & 4) << 1) | ((k & 8) >> 1); return ((kk >> 3) * 4 + (c >> 5)) * 512 + ((kk & 7) * 32 + (c & 31)) * 2; }
; DI int v_rd_base(int lane) { return ((lane & 3) << 3) | (((lane >> 2) & 3) << 6) | (((lane >> 4) & 1) << 5) | (((lane >> 5) & 1) << 8); }
; template <int OFF> DI s16x4 tr_read(int vb) { s16x4 r; asm volatile("ds_read_b64_tr_b16 %0, %1 offset:%2" : "=&v"(r) : "v"(vb), "i"(OFF) : "memory"); return r; }
; template <int D0> DI void pv_one(f32x16& od, int vb, bf16x8 pa0, bf16x8 pa1, bf16x8 pa2, bf16x8 pa3) {
;     const s16x4 l0 = tr_read<v_rd_off(D0, 0, 0)>(vb), h0 = tr_read<v_rd_off(D0, 0, 1)>(vb), l1 = tr_read<v_rd_off(D0, 1, 0)>(vb), h1 = tr_read<v_rd_off(D0, 1, 1)>(vb);
;     const s16x4 l2 = tr_read<v_rd_off(D0, 2, 0)>(vb), h2 = tr_read<v_rd_off(D0, 2, 1)>(vb), l3 = tr_read<v_rd_off(D0, 3, 0)>(vb), h3 = tr_read<v_rd_off(D0, 3, 1)>(vb);
;     asm volatile("s_waitcnt lgkmcnt(0)" ::: "memory"); SBAR();
;     ...
;     od = MFMA32(pa0, PK(l0, h0), od);
;     od = MFMA32(pa1, PK(l1, h1), od);
;     od = MFMA32(pa2, PK(l2, h2), od);
;     od = MFMA32(pa3, PK(l3, h3), od);
;     ...
; }
; DI float pv_d0_sm(f32x16* o, int vb, bf16x8 pa0, bf16x8 pa1, bf16x8 pa2, bf16x8 pa3, f32x16& q0, f32x16& q1) {
	v_mfma_f32_32x32x16_bf16 v[96:111], v[140:143], v[112:115], v[96:111]
	v_cvt_pk_bf16_f32 v129, v78, v79
	v_permlane32_swap_b32_e32 v116, v118
	v_permlane32_swap_b32_e32 v117, v119
	v_permlane32_swap_b32_e32 v126, v128
	s_waitcnt lgkmcnt(0)
	v_mfma_f32_32x32x16_bf16 v[80:95], v[212:215], v[112:115], v[80:95]
	v_permlane32_swap_b32_e32 v127, v129
	ds_read_b64_tr_b16 v[66:67], v175 offset:0
	ds_read_b64_tr_b16 v[68:69], v175 offset:0x800
	ds_read_b64_tr_b16 v[70:71], v175 offset:0x1000
	ds_read_b64_tr_b16 v[72:73], v175 offset:0x1800
	ds_read_b64_tr_b16 v[112:113], v175 offset:0x2000
	ds_read_b64_tr_b16 v[114:115], v175 offset:0x2800
	ds_read_b64_tr_b16 v[130:131], v175 offset:0x3000
	ds_read_b64_tr_b16 v[132:133], v175 offset:0x3800
	s_waitcnt lgkmcnt(0)
	s_nop 0
	v_mfma_f32_32x32x16_bf16 v[0:15], v[74:77], v[66:69], v[0:15]
	s_nop 3
	v_max_f32_e32 v64, v97, v97
	v_max_f32_e32 v66, v96, v96
	v_max_f32_e32 v64, v66, v64
	ds_read_b64_tr_b16 v[66:67], v175 offset:0x200
	ds_read_b64_tr_b16 v[68:69], v175 offset:0xa00
	v_max3_f32 v64, v64, v98, v99
	v_max3_f32 v64, v64, v100, v101
	v_mfma_f32_32x32x16_bf16 v[0:15], v[122:125], v[70:73], v[0:15]
	ds_read_b64_tr_b16 v[70:71], v175 offset:0x1200
	ds_read_b64_tr_b16 v[72:73], v175 offset:0x1a00
	ds_read_b64_tr_b16 v[134:135], v175 offset:0x2200
	ds_read_b64_tr_b16 v[136:137], v175 offset:0x2a00
	v_max3_f32 v64, v64, v102, v103
	ds_read_b64_tr_b16 v[138:139], v175 offset:0x3200
	v_max3_f32 v64, v64, v104, v105
	v_mfma_f32_32x32x16_bf16 v[0:15], v[116:119], v[112:115], v[0:15]
	ds_read_b64_tr_b16 v[140:141], v175 offset:0x3a00
	v_max3_f32 v64, v64, v106, v107
	s_waitcnt lgkmcnt(0)
	v_max3_f32 v64, v64, v108, v109
	v_max3_f32 v64, v64, v110, v111
	v_mfma_f32_32x32x16_bf16 v[0:15], v[126:129], v[130:133], v[0:15]
	v_mfma_f32_32x32x16_bf16 v[48:63], v[74:77], v[66:69], v[48:63]
	v_max3_f32 v64, v64, v80, v81
	v_max3_f32 v64, v64, v82, v83
	v_max3_f32 v64, v64, v84, v85
	v_max3_f32 v64, v64, v86, v87
	v_max3_f32 v64, v64, v88, v89
	v_max3_f32 v64, v64, v90, v91
	v_max3_f32 v64, v64, v92, v93
	v_mfma_f32_32x32x16_bf16 v[48:63], v[122:125], v[70:73], v[48:63]
	v_max3_f32 v64, v64, v94, v95
	v_mov_b32_e32 v66, v64
	s_nop 1
	v_permlane32_swap_b32_e32 v64, v66
	v_max_f32_e32 v66, v66, v66
	v_max_f32_e32 v64, v64, v64
	v_max_f32_e32 v112, v64, v66
	v_mfma_f32_32x32x16_bf16 v[48:63], v[116:119], v[134:137], v[48:63]
	ds_read_b64_tr_b16 v[66:67], v175 offset:0x400
	ds_read_b64_tr_b16 v[68:69], v175 offset:0xc00
	ds_read_b64_tr_b16 v[130:131], v175 offset:0x1400
	ds_read_b64_tr_b16 v[132:133], v175 offset:0x1c00
	ds_read_b64_tr_b16 v[134:135], v175 offset:0x2400
	ds_read_b64_tr_b16 v[136:137], v175 offset:0x2c00
	ds_read_b64_tr_b16 v[156:157], v175 offset:0x3400
	v_mfma_f32_32x32x16_bf16 v[48:63], v[126:129], v[138:141], v[48:63]
	ds_read_b64_tr_b16 v[158:159], v175 offset:0x3c00
	s_waitcnt lgkmcnt(0)
	v_mfma_f32_32x32x16_bf16 v[16:31], v[74:77], v[66:69], v[16:31]
	v_exp_f32_e32 v70, v96
	v_exp_f32_e32 v71, v97
	ds_read_b64_tr_b16 v[96:97], v175 offset:0x600
	v_exp_f32_e32 v72, v98
	v_exp_f32_e32 v73, v99
	ds_read_b64_tr_b16 v[98:99], v175 offset:0xe00
	v_exp_f32_e32 v68, v100
	v_mfma_f32_32x32x16_bf16 v[16:31], v[122:125], v[130:133], v[16:31]
	v_exp_f32_e32 v69, v101
	ds_read_b64_tr_b16 v[100:101], v175 offset:0x1600
	v_exp_f32_e32 v66, v102
	v_exp_f32_e32 v67, v103
	ds_read_b64_tr_b16 v[102:103], v175 offset:0x1e00
	ds_read_b64_tr_b16 v[130:131], v175 offset:0x2600
	ds_read_b64_tr_b16 v[132:133], v175 offset:0x2e00
	v_mfma_f32_32x32x16_bf16 v[16:31], v[116:119], v[134:137], v[16:31]
	ds_read_b64_tr_b16 v[134:135], v175 offset:0x3600
	ds_read_b64_tr_b16 v[136:137], v175 offset:0x3e00
	s_waitcnt lgkmcnt(0)
	v_mfma_f32_32x32x16_bf16 v[16:31], v[126:129], v[156:159], v[16:31]
	v_mfma_f32_32x32x16_bf16 v[32:47], v[74:77], v[96:99], v[32:47]
	v_exp_f32_e32 v96, v104
	v_exp_f32_e32 v97, v105
	v_exp_f32_e32 v76, v106
	v_exp_f32_e32 v77, v107
	v_exp_f32_e32 v78, v108
	v_exp_f32_e32 v79, v109
	v_exp_f32_e32 v74, v110
	v_mfma_f32_32x32x16_bf16 v[32:47], v[122:125], v[100:103], v[32:47]
	v_exp_f32_e32 v75, v111
	v_cmp_ge_f32_e32 vcc, s82, v112
	v_mov_b32_e32 v64, 1.0
	s_cmp_eq_u64 vcc, exec
	v_mfma_f32_32x32x16_bf16 v[32:47], v[116:119], v[130:133], v[32:47]
	v_mfma_f32_32x32x16_bf16 v[32:47], v[126:129], v[134:137], v[32:47]
	s_cbranch_scc0 .LBB0_638
	.p2align 6

; DI void dn_scan_item(const Params& p, int seqbase, int T, int h, int dir, char* lds) {
;     ...
;     f32x16 S[4];
; #pragma unroll
;     for (int d = 0; d < 4; ++d)
; #pragma unroll
;         for (int i = 0; i < 16; ++i) S[d][i] = 0.f;
;     const int slab = wid & 3;
;     struct URegs { u32x4 un[2][2]; float gl; };
;     auto uload = [&](int n, URegs& U) {
;         int lane = lane0; asm volatile("" : "+v"(lane));
;         const int cn = dir ? N - 1 - n : n; const size_t ci = (size_t)((gch0 + cn) * 4 + h) * 2 + dir;
;         const bf16_t* Uc = UcB + ci * 8192;
; #pragma unroll
;         for (int pt = 0; pt < 2; ++pt) { const u32x4* sp = (const u32x4*)(Uc + ((slab * 2 + pt) * 64 + lane) * 16); U.un[pt][0] = sp[0]; U.un[pt][1] = sp[1]; }
;         U.gl = GcB[ci * 64 + 63];
;     };
;     ...
;         URegs UA, UB;
;         uload(0, UA); uload(1, UB);
;         __syncthreads();
.LBB0_603:
	s_and_b64 vcc, exec, s[2:3]
	s_cbranch_vccz .LBB0_620
	v_mov_b32_e32 v183, v192
	s_lshl_b32 s2, s96, 8
	s_add_i32 s15, s2, 0x7ffdf000
	v_readfirstlane_b32 s12, v183
	s_bfe_u32 s26, s96, 0x20001
	s_and_b32 s14, s96, 1
	s_ashr_i32 s16, s12, 6
	s_cmp_eq_u32 s14, 0
	s_cselect_b64 s[2:3], -1, 0
	s_lshr_b32 s15, s15, 6
	s_and_b32 s27, s15, 0x1ffffe0
	s_cmp_lt_i32 s16, 4
	s_mov_b64 s[16:17], -1
	s_waitcnt vmcnt(63) expcnt(7) lgkmcnt(15)
	s_barrier
	s_cbranch_scc0 .LBB0_612
	s_bfe_u32 s22, s12, 0x20006
	s_and_b64 s[16:17], s[2:3], exec
	s_cselect_b32 s12, s87, 0x38220000
	s_add_u32 s23, s28, s12
	s_addc_u32 s24, s29, 0
	s_and_b64 s[16:17], s[2:3], exec
	s_cselect_b32 s12, 0, 31
	s_or_b32 s12, s27, s12
	s_lshl_b32 s12, s12, 3
	s_lshl_b32 s25, s26, 1
	s_or_b32 s12, s12, s25
	s_or_b32 s12, s12, s14
	v_and_b32_e32 v204, 63, v183
	s_lshl_b64 s[18:19], s[12:13], 14
	v_mov_b32_e32 v0, v204
	s_add_u32 s20, s76, s18
	s_addc_u32 s21, s77, s19
	s_lshl_b32 s17, s22, 11
	v_lshlrev_b32_e32 v2, 4, v0
	v_add_u32_e32 v0, s17, v2
	v_ashrrev_i32_e32 v1, 31, v0
	v_lshl_add_u64 v[0:1], v[0:1], 1, s[20:21]
	s_or_b32 s18, s17, 0x400
	global_load_dwordx4 v[72:75], v[0:1], off offset:16
	global_load_dwordx4 v[76:79], v[0:1], off
	v_add_u32_e32 v0, s18, v2
	v_ashrrev_i32_e32 v1, 31, v0
	v_lshl_add_u64 v[0:1], v[0:1], 1, s[20:21]
	s_lshl_b64 s[20:21], s[12:13], 8
	s_add_u32 s20, s78, s20
	s_addc_u32 s21, s79, s21
	global_load_dwordx4 v[64:67], v[0:1], off offset:16
	global_load_dwordx4 v[68:71], v[0:1], off
	global_load_dword v80, v185, s[20:21] offset:252
	s_and_b64 s[20:21], s[2:3], exec
	s_cselect_b32 s12, 1, 30
	s_or_b32 s12, s27, s12
	s_lshl_b32 s12, s12, 3
	s_or_b32 s12, s12, s25
	v_mov_b32_e32 v0, v204
	s_or_b32 s12, s12, s14
	s_lshl_b64 s[20:21], s[12:13], 14
	v_lshlrev_b32_e32 v2, 4, v0
	s_add_u32 s20, s76, s20
	v_add_u32_e32 v0, s17, v2
	s_addc_u32 s21, s77, s21
	v_ashrrev_i32_e32 v1, 31, v0
	v_lshl_add_u64 v[0:1], v[0:1], 1, s[20:21]
	global_load_dwordx4 v[152:155], v[0:1], off offset:16
	global_load_dwordx4 v[156:159], v[0:1], off
	v_add_u32_e32 v0, s18, v2
	v_ashrrev_i32_e32 v1, 31, v0
	v_lshl_add_u64 v[0:1], v[0:1], 1, s[20:21]
	s_lshl_b64 s[20:21], s[12:13], 8
	s_add_u32 s20, s78, s20
	s_addc_u32 s21, s79, s21
	global_load_dwordx4 v[144:147], v[0:1], off offset:16
	global_load_dwordx4 v[148:151], v[0:1], off
	global_load_dword v206, v185, s[20:21] offset:252
	s_lshl_b32 s12, s26, 8
	s_add_u32 s12, s23, s12
	s_addc_u32 s20, s24, 0
	s_lshl_b32 s19, s22, 6
	s_add_u32 s19, s12, s19
	v_mov_b32_e32 v0, 0
	s_mov_b32 s15, 31
	s_mov_b32 s16, 3
	s_addc_u32 s20, s20, 0
	s_and_b32 s21, s96, 7
	v_mov_b32_e32 v1, v0
	v_mov_b32_e32 v2, v0
	v_mov_b32_e32 v3, v0
	s_waitcnt vmcnt(27)
	v_mov_b32_e32 v4, v0
	v_mov_b32_e32 v5, v0
	v_mov_b32_e32 v6, v0
	v_mov_b32_e32 v7, v0
	s_waitcnt vmcnt(26)
	v_mov_b32_e32 v8, v0
	v_mov_b32_e32 v9, v0
	v_mov_b32_e32 v10, v0
	v_mov_b32_e32 v11, v0
	s_waitcnt vmcnt(24)
	v_mov_b32_e32 v12, v0
	v_mov_b32_e32 v13, v0
	v_mov_b32_e32 v14, v0
	v_mov_b32_e32 v15, v0
	s_waitcnt vmcnt(23)
	v_mov_b32_e32 v16, v0
	v_mov_b32_e32 v17, v0
	v_mov_b32_e32 v18, v0
	v_mov_b32_e32 v19, v0
	s_waitcnt vmcnt(22)
	v_mov_b32_e32 v20, v0
	v_mov_b32_e32 v21, v0
	v_mov_b32_e32 v22, v0
	v_mov_b32_e32 v23, v0
	s_waitcnt vmcnt(20)
	v_mov_b32_e32 v24, v0
	v_mov_b32_e32 v25, v0
	v_mov_b32_e32 v26, v0
	v_mov_b32_e32 v27, v0
	s_waitcnt vmcnt(19)
	v_mov_b32_e32 v28, v0
	v_mov_b32_e32 v29, v0
	v_mov_b32_e32 v30, v0
	v_mov_b32_e32 v31, v0
	s_waitcnt vmcnt(18)
	v_mov_b32_e32 v32, v0
	v_mov_b32_e32 v33, v0
	v_mov_b32_e32 v34, v0
	v_mov_b32_e32 v35, v0
	s_waitcnt vmcnt(16)
	v_mov_b32_e32 v36, v0
	s_waitcnt vmcnt(9)
	v_mov_b64_e32 v[130:131], v[74:75]
	s_waitcnt vmcnt(8)
	v_mov_b64_e32 v[134:135], v[78:79]
	v_mov_b32_e32 v37, v0
	v_mov_b32_e32 v38, v0
	v_mov_b32_e32 v39, v0
	v_mov_b32_e32 v40, v0
	v_mov_b32_e32 v41, v0
	s_waitcnt vmcnt(7)
	v_mov_b64_e32 v[138:139], v[66:67]
	s_waitcnt vmcnt(6)
	v_mov_b64_e32 v[142:143], v[70:71]
	v_mov_b32_e32 v42, v0
	v_mov_b32_e32 v43, v0
	v_mov_b32_e32 v44, v0
	v_mov_b32_e32 v45, v0
	v_mov_b32_e32 v46, v0
	v_mov_b32_e32 v47, v0
	v_mov_b32_e32 v48, v0
	v_mov_b32_e32 v49, v0
	v_mov_b32_e32 v50, v0
	v_mov_b32_e32 v51, v0
	v_mov_b32_e32 v52, v0
	v_mov_b32_e32 v53, v0
	v_mov_b32_e32 v54, v0
	v_mov_b32_e32 v55, v0
	v_mov_b32_e32 v56, v0
	v_mov_b32_e32 v57, v0
	v_mov_b32_e32 v58, v0
	v_mov_b32_e32 v59, v0
	v_mov_b32_e32 v60, v0
	v_mov_b32_e32 v61, v0
	v_mov_b32_e32 v62, v0
	v_mov_b32_e32 v63, v0
	s_waitcnt vmcnt(5)
	v_mov_b32_e32 v205, v80
	v_mov_b64_e32 v[136:137], v[64:65]
	v_mov_b64_e32 v[140:141], v[68:69]
	v_mov_b64_e32 v[128:129], v[72:73]
	v_mov_b64_e32 v[132:133], v[76:77]
	s_barrier
	s_branch .LBB0_607
	.p2align 6

; DI void dn_scan_item(const Params& p, int seqbase, int T, int h, int dir, char* lds) {
;     ...
;     f32x16 S[4];
; #pragma unroll
;     for (int d = 0; d < 4; ++d)
; #pragma unroll
;         for (int i = 0; i < 16; ++i) S[d][i] = 0.f;
;     const int slab = wid & 3;
;     struct URegs { u32x4 un[2][2]; float gl; };
;     auto uload = [&](int n, URegs& U) {
;         int lane = lane0; asm volatile("" : "+v"(lane));
;         const int cn = dir ? N - 1 - n : n; const size_t ci = (size_t)((gch0 + cn) * 4 + h) * 2 + dir;
;         const bf16_t* Uc = UcB + ci * 8192;
; #pragma unroll
;         for (int pt = 0; pt < 2; ++pt) { const u32x4* sp = (const u32x4*)(Uc + ((slab * 2 + pt) * 64 + lane) * 16); U.un[pt][0] = sp[0]; U.un[pt][1] = sp[1]; }
;         U.gl = GcB[ci * 64 + 63];
;     };
;     ...
;         URegs UA, UB;
;         uload(0, UA); uload(1, UB);
;         __syncthreads();
.LBB0_621:
	s_andn2_b64 vcc, exec, s[2:3]
	s_cbranch_vccnz .LBB0_566
	s_lshl_b32 s2, s96, 11
	v_mov_b32_e32 v183, v192
	s_and_b32 s2, s2, 0xffffc000
	s_add_i32 s14, s2, 0x10000
	v_readfirstlane_b32 s16, v183
	s_bfe_u32 s24, s96, 0x20001
	s_and_b32 s12, s96, 1
	s_ashr_i32 s15, s16, 6
	s_cmp_eq_u32 s12, 0
	s_cselect_b64 s[2:3], -1, 0
	s_ashr_i32 s25, s14, 6
	s_cmp_lt_i32 s15, 4
	s_mov_b64 s[14:15], -1
	s_waitcnt vmcnt(63) expcnt(7) lgkmcnt(15)
	s_barrier
	s_cbranch_scc0 .LBB0_630
	s_bfe_u32 s22, s16, 0x20006
	s_and_b64 s[14:15], s[2:3], exec
	s_cselect_b32 s14, s87, 0x38220000
	s_add_u32 s23, s28, s14
	s_addc_u32 s26, s29, 0
	s_and_b64 s[16:17], s[2:3], exec
	s_cselect_b32 s15, 0, 0xff
	s_or_b32 s15, s25, s15
	s_lshl_b32 s15, s15, 2
	s_or_b32 s16, s15, s24
	s_ashr_i32 s17, s16, 31
	s_lshl_b64 s[18:19], s[16:17], 1
	s_or_b32 s18, s18, s12
	v_and_b32_e32 v204, 63, v183
	s_lshl_b64 s[16:17], s[18:19], 14
	s_waitcnt vmcnt(18)
	v_mov_b32_e32 v0, v204
	s_add_u32 s20, s76, s16
	s_addc_u32 s21, s77, s17
	s_lshl_b32 s15, s22, 11
	v_lshlrev_b32_e32 v2, 4, v0
	v_add_u32_e32 v0, s15, v2
	v_ashrrev_i32_e32 v1, 31, v0
	v_lshl_add_u64 v[0:1], v[0:1], 1, s[20:21]
	s_or_b32 s16, s15, 0x400
	global_load_dwordx4 v[72:75], v[0:1], off offset:16
	global_load_dwordx4 v[76:79], v[0:1], off
	v_add_u32_e32 v0, s16, v2
	s_lshl_b64 s[18:19], s[18:19], 8
	v_ashrrev_i32_e32 v1, 31, v0
	s_add_u32 s18, s78, s18
	v_lshl_add_u64 v[0:1], v[0:1], 1, s[20:21]
	s_addc_u32 s19, s79, s19
	global_load_dwordx4 v[64:67], v[0:1], off offset:16
	global_load_dwordx4 v[68:71], v[0:1], off
	global_load_dword v80, v185, s[18:19] offset:252
	s_and_b64 s[18:19], s[2:3], exec
	s_cselect_b32 s17, 1, 0xfe
	s_or_b32 s17, s25, s17
	s_lshl_b32 s17, s17, 2
	s_or_b32 s18, s17, s24
	s_ashr_i32 s19, s18, 31
	s_lshl_b64 s[18:19], s[18:19], 1
	v_mov_b32_e32 v0, v204
	s_or_b32 s18, s18, s12
	s_lshl_b64 s[20:21], s[18:19], 14
	v_lshlrev_b32_e32 v2, 4, v0
	s_add_u32 s20, s76, s20
	v_add_u32_e32 v0, s15, v2
	s_addc_u32 s21, s77, s21
	v_ashrrev_i32_e32 v1, 31, v0
	v_lshl_add_u64 v[0:1], v[0:1], 1, s[20:21]
	global_load_dwordx4 v[152:155], v[0:1], off offset:16
	global_load_dwordx4 v[156:159], v[0:1], off
	v_add_u32_e32 v0, s16, v2
	s_lshl_b64 s[18:19], s[18:19], 8
	v_ashrrev_i32_e32 v1, 31, v0
	s_add_u32 s18, s78, s18
	v_lshl_add_u64 v[0:1], v[0:1], 1, s[20:21]
	s_addc_u32 s19, s79, s19
	global_load_dwordx4 v[144:147], v[0:1], off offset:16
	global_load_dwordx4 v[148:151], v[0:1], off
	global_load_dword v206, v185, s[18:19] offset:252
	s_lshl_b32 s17, s24, 8
	s_add_u32 s17, s23, s17
	s_addc_u32 s18, s26, 0
	s_lshl_b32 s19, s22, 6
	s_add_u32 s17, s17, s19
	v_mov_b32_e32 v0, 0
	s_movk_i32 s14, 0xff
	s_addc_u32 s18, s18, 0
	s_mov_b32 s19, 3
	v_mov_b32_e32 v1, v0
	v_mov_b32_e32 v2, v0
	v_mov_b32_e32 v3, v0
	s_waitcnt vmcnt(27)
	v_mov_b32_e32 v4, v0
	v_mov_b32_e32 v5, v0
	v_mov_b32_e32 v6, v0
	v_mov_b32_e32 v7, v0
	s_waitcnt vmcnt(26)
	v_mov_b32_e32 v8, v0
	v_mov_b32_e32 v9, v0
	v_mov_b32_e32 v10, v0
	v_mov_b32_e32 v11, v0
	s_waitcnt vmcnt(24)
	v_mov_b32_e32 v12, v0
	v_mov_b32_e32 v13, v0
	v_mov_b32_e32 v14, v0
	v_mov_b32_e32 v15, v0
	s_waitcnt vmcnt(23)
	v_mov_b32_e32 v16, v0
	v_mov_b32_e32 v17, v0
	v_mov_b32_e32 v18, v0
	v_mov_b32_e32 v19, v0
	s_waitcnt vmcnt(22)
	v_mov_b32_e32 v20, v0
	v_mov_b32_e32 v21, v0
	v_mov_b32_e32 v22, v0
	v_mov_b32_e32 v23, v0
	s_waitcnt vmcnt(20)
	v_mov_b32_e32 v24, v0
	v_mov_b32_e32 v25, v0
	v_mov_b32_e32 v26, v0
	v_mov_b32_e32 v27, v0
	s_waitcnt vmcnt(19)
	v_mov_b32_e32 v28, v0
	v_mov_b32_e32 v29, v0
	v_mov_b32_e32 v30, v0
	v_mov_b32_e32 v31, v0
	s_waitcnt vmcnt(18)
	v_mov_b32_e32 v32, v0
	v_mov_b32_e32 v33, v0
	v_mov_b32_e32 v34, v0
	v_mov_b32_e32 v35, v0
	s_waitcnt vmcnt(9)
	v_mov_b64_e32 v[130:131], v[74:75]
	s_waitcnt vmcnt(8)
	v_mov_b64_e32 v[134:135], v[78:79]
	v_mov_b32_e32 v36, v0
	v_mov_b32_e32 v37, v0
	v_mov_b32_e32 v38, v0
	v_mov_b32_e32 v39, v0
	v_mov_b32_e32 v40, v0
	s_waitcnt vmcnt(7)
	v_mov_b64_e32 v[138:139], v[66:67]
	s_waitcnt vmcnt(6)
	v_mov_b64_e32 v[142:143], v[70:71]
	v_mov_b32_e32 v41, v0
	v_mov_b32_e32 v42, v0
	v_mov_b32_e32 v43, v0
	v_mov_b32_e32 v44, v0
	v_mov_b32_e32 v45, v0
	v_mov_b32_e32 v46, v0
	v_mov_b32_e32 v47, v0
	v_mov_b32_e32 v48, v0
	v_mov_b32_e32 v49, v0
	v_mov_b32_e32 v50, v0
	v_mov_b32_e32 v51, v0
	v_mov_b32_e32 v52, v0
	v_mov_b32_e32 v53, v0
	v_mov_b32_e32 v54, v0
	v_mov_b32_e32 v55, v0
	v_mov_b32_e32 v56, v0
	v_mov_b32_e32 v57, v0
	v_mov_b32_e32 v58, v0
	v_mov_b32_e32 v59, v0
	v_mov_b32_e32 v60, v0
	v_mov_b32_e32 v61, v0
	v_mov_b32_e32 v62, v0
	v_mov_b32_e32 v63, v0
	s_waitcnt vmcnt(5)
	v_mov_b32_e32 v205, v80
	v_mov_b64_e32 v[136:137], v[64:65]
	v_mov_b64_e32 v[140:141], v[68:69]
	v_mov_b64_e32 v[128:129], v[72:73]
	v_mov_b64_e32 v[132:133], v[76:77]
	s_barrier
	s_branch .LBB0_625
	.p2align 6

; #define PG8_STAGE(bufoff, gbase, voff) do { _Pragma("unroll") for (int _i = 0; _i < 2; ++_i) \
;         __builtin_amdgcn_global_load_lds((const unsigned*)((const char*)(gbase) + (voff)[_i]), (PG8_LAS unsigned*)(lds + (bufoff) + ldsw + _i * 8192), 16, 0, 0); } while (0)
; #define PG8_WAIT_V(n) asm volatile("s_waitcnt vmcnt(" #n ")" ::: "memory")
; #define PG8_BAR __builtin_amdgcn_s_barrier()
; template <class Epi, class Sched, bool ALIGN_EPI = false, bool SP2 = false>
; __device__ __forceinline__ void gemm_phase(PG8_LAS unsigned char* lds, const Gemm g, const Sched& S, const Epi& E) {
;     const int tid = threadIdx.x, wid = __builtin_amdgcn_readfirstlane(tid >> 6), lane = tid & 63, wr = wid >> 2, wc = wid & 3, fr = lane & 15, fq = lane >> 4;
;     const int K = g.K, nt = K / BK;
;     unsigned voffA[2], voffB[2];
; #pragma unroll
;     for (int i = 0; i < 2; ++i) { int R, C; stage_rc(tid * 16 + i * 8192, R, C); const int Rb = Epi::PERM ? ((R & ~31) + perm32(R & 31)) : R;
;         voffA[i] = (unsigned)(R * K + C) * 2u; voffB[i] = (unsigned)(Rb * K + C) * 2u; }
;     const size_t kstep = (size_t)(BK * 2);
;     const size_t hstep = (size_t)HALF * K * 2;
;     const size_t tstep = 2 * hstep;
;     const unsigned ldsw = (unsigned)wid * 1024u;
;     const int aoff = lds_byte(wr * 64 + fr, fq * 8), boff = lds_byte(wc * 32 + fr, fq * 8);
;     ...
;     if constexpr (SP2) {
;         PG8_STAGE(PG8_SB(0, 0), cB, voffB); PG8_STAGE(PG8_SB(0, 1), cB + hstep, voffB); PG8_STAGE(PG8_SA(0, 0), cA, voffA); PG8_STAGE(PG8_SA(0, 1), cA + hstep, voffA);
;         if (wr == 1) PG8_BAR;
;         PG8_WAIT_V(2); PG8_BAR;
;         PG8_STAGE(PG8_SB(1, 0), cB + kstep, voffB); PG8_STAGE(PG8_SA(1, 0), cA + kstep, voffA); PG8_STAGE(PG8_SB(1, 1), cB + hstep + kstep, voffB);
;         PG8_WAIT_V(6); PG8_BAR;
.LBB0_663:
	s_lshl_b32 s3, s3, 5
	s_mov_b64 s[22:23], 0x80
	s_and_b32 s36, s3, 0x60
	s_add_i32 m0, s5, 0x18000
	v_lshl_add_u64 v[6:7], v[6:7], 0, s[22:23]
	s_lshl_b32 s25, s2, 13
	s_lshl_b32 s3, s36, 7
	s_waitcnt vmcnt(2)
	s_barrier
	global_load_lds_dwordx4 v[6:7], off
	v_lshl_add_u64 v[4:5], v[4:5], 0, s[22:23]
	s_add_i32 m0, s5, 0x1a000
	s_add_i32 s56, s5, 0x8000
	s_add_i32 s57, s5, 0xa000
	global_load_lds_dwordx4 v[4:5], off
	v_lshl_add_u64 v[0:1], v[0:1], 0, s[22:23]
	s_mov_b32 m0, s56
	s_add_u32 s26, s16, 0x40080
	global_load_lds_dwordx4 v[0:1], off
	v_lshl_add_u64 v[0:1], v[2:3], 0, s[22:23]
	s_mov_b32 m0, s57
	s_addc_u32 s27, s17, 0
	global_load_lds_dwordx4 v[0:1], off
	s_add_i32 m0, s5, 0x1c000
	v_lshl_add_u64 v[0:1], s[26:27], 0, v[178:179]
	global_load_lds_dwordx4 v[0:1], off
	v_lshl_add_u64 v[0:1], s[26:27], 0, v[182:183]
	s_add_i32 m0, s5, 0x1e000
	v_lshl_or_b32 v142, s2, 6, v189
	global_load_lds_dwordx4 v[0:1], off
	v_bfe_u32 v0, v192, 4, 2
	v_lshlrev_b32_e32 v1, 4, v0
	v_lshl_or_b32 v2, v189, 6, v1
	v_or_b32_e32 v1, v1, v201
	v_bitop3_b32 v143, s3, v1, v202 bitop3:0xf6
	v_cmp_eq_u32_e64 s[2:3], 0, v0
	v_lshl_or_b32 v144, v0, 3, s36
	v_lshlrev_b32_e32 v0, 8, v192
	v_and_b32_e32 v0, 0x38000, v0
	v_lshlrev_b32_e32 v1, 11, v197
	v_or3_b32 v0, v186, v0, v1
	v_lshlrev_b32_e32 v3, 2, v189
	v_add_u32_e32 v130, v0, v187
	v_lshlrev_b32_e32 v0, 4, v198
	v_and_b32_e32 v3, 32, v3
	s_waitcnt vmcnt(6)
	s_cmpk_lt_u32 s24, 0x100
	v_and_b32_e32 v0, 0x78000, v0
	v_bitop3_b32 v2, v2, s25, v3 bitop3:0xde
	s_cselect_b64 s[24:25], -1, 0
	v_or3_b32 v0, v186, v0, v1
	s_add_i32 s60, 0, 0x10000
	s_add_i32 s61, 0, 0x14000
	v_mov_b32_e32 v131, v129
	v_add_u32_e32 v132, v0, v187
	v_mov_b32_e32 v133, v129
	v_add_u32_e32 v145, s60, v143
	v_add_u32_e32 v146, s61, v143
	v_add_u32_e32 v147, 0, v2
	s_mov_b32 s62, 0xffff
	s_barrier
	s_branch .LBB0_666
	.p2align 6
.LBB0_664:
	s_mov_b64 s[26:27], 0
	.p2align 6

; template <class Epi, class Sched, bool ALIGN_EPI = false, bool SP2 = false>
; __device__ __forceinline__ void gemm_phase(PG8_LAS unsigned char* lds, const Gemm g, const Sched& S, const Epi& E) {
;     ...
;         const bool has_next = S.next(ui + 1, nxt);
;         const char* nA = has_next ? (const char*)g.A + (size_t)nxt.pm * tstep : cA; const char* nB = has_next ? (const char*)g.Bt + (size_t)nxt.pn * tstep : cB;
;         for (int t = 0; t < nt; t += 2) {
;             const bool last = (t == nt - 2);
;             const char* a1 = cA + (size_t)(t + 1) * kstep;
;             const char* a2 = last ? nA : cA + (size_t)(t + 2) * kstep; const char* b2 = last ? nB : cB + (size_t)(t + 2) * kstep;
;     ...
; #pragma unroll
;         for (int a = 0; a < 2; ++a)
; #pragma unroll
;             for (int b = 0; b < 2; ++b)
; #pragma unroll
;                 for (int m = 0; m < 4; ++m)
; #pragma unroll
;                     for (int n = 0; n < 2; ++n) acc[a][b][m][n] = (f32x4){0.f, 0.f, 0.f, 0.f};
;         cur = nxt; cA = nA; cB = nB; ++ui;
.LBB0_666:
	s_add_i32 s51, s51, 1
	s_mov_b64 s[36:37], s[18:19]
	s_mov_b32 s18, s4
	s_mov_b32 s64, s4
	s_mul_i32 s4, s51, s33
	s_mov_b32 s19, s14
	s_mov_b32 s63, s14
	s_add_i32 s14, s4, s70
	s_cmpk_lt_u32 s14, 0xc0
	s_mov_b64 s[38:39], s[16:17]
	s_cselect_b64 s[26:27], -1, 0
	s_lshr_b32 s4, s14, 2
	s_and_b32 s16, s14, 3
	s_and_b32 s4, s4, 60
	s_or_b32 s16, s16, s73
	s_add_i32 s4, s16, s4
	s_bfe_u32 s14, s14, 0x20002
	s_and_b64 s[16:17], s[26:27], exec
	s_cselect_b32 s18, s4, s18
	s_cselect_b32 s16, s14, s19
	s_ashr_i32 s19, s18, 31
	s_lshl_b64 s[18:19], s[18:19], 19
	s_add_u32 s18, s48, s18
	s_addc_u32 s19, s49, s19
	s_and_b64 s[40:41], s[26:27], exec
	s_cselect_b32 s65, s19, s37
	s_cselect_b32 s66, s18, s36
	s_ashr_i32 s17, s16, 31
	s_lshl_b64 s[16:17], s[16:17], 19
	s_add_u32 s16, s42, s16
	s_addc_u32 s17, s43, s17
	s_and_b64 s[40:41], s[26:27], exec
	s_cselect_b32 s67, s17, s39
	s_cselect_b32 s68, s16, s38
	s_add_u32 s36, s36, 0x40080
	s_addc_u32 s37, s37, 0
	s_add_u32 s69, s38, 0x100
	v_mov_b32_e32 v0, 0
	s_addc_u32 s72, s39, 0
	s_mov_b32 s74, -2
	s_waitcnt lgkmcnt(0)
	v_mov_b32_e32 v1, v0
	v_mov_b32_e32 v2, v0
	v_mov_b32_e32 v3, v0
	v_mov_b32_e32 v4, v0
	v_mov_b32_e32 v5, v0
	v_mov_b32_e32 v6, v0
	v_mov_b32_e32 v7, v0
	v_mov_b32_e32 v16, v0
	v_mov_b32_e32 v17, v0
	v_mov_b32_e32 v18, v0
	v_mov_b32_e32 v19, v0
	v_mov_b32_e32 v20, v0
	v_mov_b32_e32 v21, v0
	v_mov_b32_e32 v22, v0
	v_mov_b32_e32 v23, v0
	v_mov_b32_e32 v32, v0
	v_mov_b32_e32 v33, v0
	v_mov_b32_e32 v34, v0
	v_mov_b32_e32 v35, v0
	v_mov_b32_e32 v36, v0
	v_mov_b32_e32 v37, v0
	v_mov_b32_e32 v38, v0
	v_mov_b32_e32 v39, v0
	v_mov_b32_e32 v48, v0
	v_mov_b32_e32 v49, v0
	v_mov_b32_e32 v50, v0
	v_mov_b32_e32 v51, v0
	v_mov_b32_e32 v52, v0
	v_mov_b32_e32 v53, v0
	v_mov_b32_e32 v54, v0
	v_mov_b32_e32 v55, v0
	v_mov_b32_e32 v8, v0
	v_mov_b32_e32 v9, v0
	v_mov_b32_e32 v10, v0
	v_mov_b32_e32 v11, v0
	v_mov_b32_e32 v12, v0
	v_mov_b32_e32 v13, v0
	v_mov_b32_e32 v14, v0
	v_mov_b32_e32 v15, v0
	v_mov_b32_e32 v24, v0
	v_mov_b32_e32 v25, v0
	v_mov_b32_e32 v26, v0
	v_mov_b32_e32 v27, v0
	v_mov_b32_e32 v28, v0
	v_mov_b32_e32 v29, v0
	v_mov_b32_e32 v30, v0
	v_mov_b32_e32 v31, v0
	v_mov_b32_e32 v40, v0
	v_mov_b32_e32 v41, v0
	v_mov_b32_e32 v42, v0
	v_mov_b32_e32 v43, v0
	v_mov_b32_e32 v44, v0
	v_mov_b32_e32 v45, v0
	v_mov_b32_e32 v46, v0
	v_mov_b32_e32 v47, v0
	v_mov_b32_e32 v56, v0
	v_mov_b32_e32 v57, v0
	v_mov_b32_e32 v58, v0
	v_mov_b32_e32 v59, v0
	v_mov_b32_e32 v60, v0
	v_mov_b32_e32 v61, v0
	v_mov_b32_e32 v62, v0
	v_mov_b32_e32 v63, v0
	v_mov_b32_e32 v64, v0
	v_mov_b32_e32 v65, v0
	v_mov_b32_e32 v66, v0
	v_mov_b32_e32 v67, v0
	v_mov_b32_e32 v68, v0
	v_mov_b32_e32 v69, v0
	v_mov_b32_e32 v70, v0
	v_mov_b32_e32 v71, v0
	v_mov_b32_e32 v80, v0
	v_mov_b32_e32 v81, v0
	v_mov_b32_e32 v82, v0
	v_mov_b32_e32 v83, v0
	v_mov_b32_e32 v84, v0
	v_mov_b32_e32 v85, v0
	v_mov_b32_e32 v86, v0
	v_mov_b32_e32 v87, v0
	v_mov_b32_e32 v96, v0
	v_mov_b32_e32 v97, v0
	v_mov_b32_e32 v98, v0
	v_mov_b32_e32 v99, v0
	v_mov_b32_e32 v100, v0
	v_mov_b32_e32 v101, v0
	v_mov_b32_e32 v102, v0
	v_mov_b32_e32 v103, v0
	v_mov_b32_e32 v112, v0
	v_mov_b32_e32 v113, v0
	v_mov_b32_e32 v114, v0
	v_mov_b32_e32 v115, v0
	v_mov_b32_e32 v116, v0
	v_mov_b32_e32 v117, v0
	v_mov_b32_e32 v118, v0
	v_mov_b32_e32 v119, v0
	v_mov_b32_e32 v72, v0
	v_mov_b32_e32 v73, v0
	v_mov_b32_e32 v74, v0
	v_mov_b32_e32 v75, v0
	v_mov_b32_e32 v76, v0
	v_mov_b32_e32 v77, v0
	v_mov_b32_e32 v78, v0
	v_mov_b32_e32 v79, v0
	v_mov_b32_e32 v88, v0
	v_mov_b32_e32 v89, v0
	v_mov_b32_e32 v90, v0
	v_mov_b32_e32 v91, v0
	v_mov_b32_e32 v92, v0
	v_mov_b32_e32 v93, v0
	v_mov_b32_e32 v94, v0
	v_mov_b32_e32 v95, v0
	v_mov_b32_e32 v104, v0
	v_mov_b32_e32 v105, v0
	v_mov_b32_e32 v106, v0
	v_mov_b32_e32 v107, v0
	v_mov_b32_e32 v108, v0
	v_mov_b32_e32 v109, v0
	v_mov_b32_e32 v110, v0
	v_mov_b32_e32 v111, v0
	v_mov_b32_e32 v120, v0
	v_mov_b32_e32 v121, v0
	v_mov_b32_e32 v122, v0
	v_mov_b32_e32 v123, v0
	v_mov_b32_e32 v124, v0
	v_mov_b32_e32 v125, v0
	v_mov_b32_e32 v126, v0
	v_mov_b32_e32 v127, v0
	.p2align 6

; #define PG8_STAGE(bufoff, gbase, voff) do { _Pragma("unroll") for (int _i = 0; _i < 2; ++_i) \
;         __builtin_amdgcn_global_load_lds((const unsigned*)((const char*)(gbase) + (voff)[_i]), (PG8_LAS unsigned*)(lds + (bufoff) + ldsw + _i * 8192), 16, 0, 0); } while (0)
; #define PG8_WAIT_V(n) asm volatile("s_waitcnt vmcnt(" #n ")" ::: "memory")
; #define PG8_BAR __builtin_amdgcn_s_barrier()
; template <class Epi, class Sched, bool ALIGN_EPI = false, bool SP2 = false>
; __device__ __forceinline__ void gemm_phase(PG8_LAS unsigned char* lds, const Gemm g, const Sched& S, const Epi& E) {
;     const int tid = threadIdx.x, wid = __builtin_amdgcn_readfirstlane(tid >> 6), lane = tid & 63, wr = wid >> 2, wc = wid & 3, fr = lane & 15, fq = lane >> 4;
;     const int K = g.K, nt = K / BK;
;     unsigned voffA[2], voffB[2];
; #pragma unroll
;     for (int i = 0; i < 2; ++i) { int R, C; stage_rc(tid * 16 + i * 8192, R, C); const int Rb = Epi::PERM ? ((R & ~31) + perm32(R & 31)) : R;
;         voffA[i] = (unsigned)(R * K + C) * 2u; voffB[i] = (unsigned)(Rb * K + C) * 2u; }
;     const size_t kstep = (size_t)(BK * 2);
;     const size_t hstep = (size_t)HALF * K * 2;
;     const size_t tstep = 2 * hstep;
;     const unsigned ldsw = (unsigned)wid * 1024u;
;     const int aoff = lds_byte(wr * 64 + fr, fq * 8), boff = lds_byte(wc * 32 + fr, fq * 8);
;     ...
;     if constexpr (SP2) {
;         PG8_STAGE(PG8_SB(0, 0), cB, voffB); PG8_STAGE(PG8_SB(0, 1), cB + hstep, voffB); PG8_STAGE(PG8_SA(0, 0), cA, voffA); PG8_STAGE(PG8_SA(0, 1), cA + hstep, voffA);
;         if (wr == 1) PG8_BAR;
;         PG8_WAIT_V(2); PG8_BAR;
;         PG8_STAGE(PG8_SB(1, 0), cB + kstep, voffB); PG8_STAGE(PG8_SA(1, 0), cA + kstep, voffA); PG8_STAGE(PG8_SB(1, 1), cB + hstep + kstep, voffB);
;         PG8_WAIT_V(6); PG8_BAR;
.LBB0_733:
	s_lshl_b32 s9, s16, 5
	s_mov_b64 s[16:17], 0x80
	s_add_i32 m0, s45, 0x18000
	v_lshl_add_u64 v[6:7], v[6:7], 0, s[16:17]
	s_lshl_b32 s5, s19, 13
	s_and_b32 s9, s9, 0x60
	s_waitcnt vmcnt(2)
	s_barrier
	global_load_lds_dwordx4 v[6:7], off
	v_lshl_add_u64 v[4:5], v[4:5], 0, s[16:17]
	s_add_i32 m0, s45, 0x1a000
	s_add_i32 s61, s45, 0x8000
	s_add_i32 s62, s45, 0xa000
	global_load_lds_dwordx4 v[4:5], off
	v_lshl_add_u64 v[0:1], v[0:1], 0, s[16:17]
	s_mov_b32 m0, s61
	s_add_u32 s20, s40, 0x40080
	global_load_lds_dwordx4 v[0:1], off
	v_lshl_add_u64 v[0:1], v[2:3], 0, s[16:17]
	s_mov_b32 m0, s62
	s_addc_u32 s21, s41, 0
	global_load_lds_dwordx4 v[0:1], off
	s_add_i32 m0, s45, 0x1c000
	v_lshl_add_u64 v[0:1], s[20:21], 0, v[178:179]
	global_load_lds_dwordx4 v[0:1], off
	v_lshl_add_u64 v[0:1], s[20:21], 0, v[182:183]
	s_add_i32 m0, s45, 0x1e000
	v_lshlrev_b32_e32 v2, 11, v197
	global_load_lds_dwordx4 v[0:1], off
	v_lshlrev_b32_e32 v1, 2, v189
	v_lshl_or_b32 v0, v189, 6, v190
	v_and_b32_e32 v1, 32, v1
	v_bitop3_b32 v0, v0, s5, v1 bitop3:0xde
	v_lshlrev_b32_e32 v1, 8, v192
	v_and_b32_e32 v1, 0x38000, v1
	v_or3_b32 v1, v186, v1, v2
	v_add_u32_e32 v128, v1, v187
	v_lshlrev_b32_e32 v1, 4, v198
	s_waitcnt vmcnt(6)
	s_cmpk_lt_u32 s18, 0x100
	v_and_b32_e32 v1, 0x78000, v1
	v_lshl_or_b32 v248, s19, 6, v189
	v_lshl_add_u32 v249, v188, 1, v189
	v_lshrrev_b32_e32 v250, 2, v249
	v_and_b32_e32 v251, 3, v249
	v_lshl_or_b32 v140, s19, 6, v250
	v_lshl_add_u32 v249, v251, 4, v250
	v_lshlrev_b32_e32 v249, 2, v249
	v_lshl_or_b32 v141, s9, 7, v191
	s_cselect_b64 s[18:19], -1, 0
	v_or3_b32 v1, v186, v1, v2
	s_add_i32 s63, 0, 0x10000
	s_add_i32 s64, 0, 0x14000
	v_lshl_or_b32 v142, v251, 3, s9
	v_mov_b32_e32 v129, v179
	v_add_u32_e32 v130, v1, v187
	v_mov_b32_e32 v131, v179
	v_add_u32_e32 v143, s63, v141
	v_add_u32_e32 v144, s64, v141
	v_add_u32_e32 v145, 0, v0
	s_movk_i32 s65, 0x2b00
	s_movk_i32 s66, 0x1580
	v_mov_b32_e32 v146, 0x358637bd
	s_mov_b32 s67, 0x800000
	s_add_i32 s68, s45, 0xc000
	s_barrier
	s_branch .LBB0_736
	.p2align 6
.LBB0_734:
	s_mov_b64 s[4:5], 0
	.p2align 6

; template <class Epi, class Sched, bool ALIGN_EPI = false, bool SP2 = false>
; __device__ __forceinline__ void gemm_phase(PG8_LAS unsigned char* lds, const Gemm g, const Sched& S, const Epi& E) {
;     ...
; #pragma unroll
;         for (int a = 0; a < 2; ++a)
; #pragma unroll
;             for (int b = 0; b < 2; ++b)
; #pragma unroll
;                 for (int m = 0; m < 4; ++m)
; #pragma unroll
;                     for (int n = 0; n < 2; ++n) acc[a][b][m][n] = (f32x4){0.f, 0.f, 0.f, 0.f};
;         cur = nxt; cA = nA; cB = nB; ++ui;
.LBB0_738:
	s_ashr_i32 s21, s20, 31
	s_lshl_b64 s[24:25], s[20:21], 19
	s_add_u32 s24, s46, s24
	s_addc_u32 s25, s47, s25
	s_and_b64 s[36:37], s[26:27], exec
	s_cselect_b32 s5, s25, s39
	s_cselect_b32 s9, s24, s38
	s_ashr_i32 s23, s22, 31
	s_lshl_b64 s[36:37], s[22:23], 19
	s_add_u32 s36, s49, s36
	s_addc_u32 s37, s50, s37
	s_and_b64 s[42:43], s[26:27], exec
	s_cselect_b32 s21, s37, s41
	s_cselect_b32 s23, s36, s40
	s_add_u32 s38, s38, 0x40080
	s_addc_u32 s39, s39, 0
	s_add_u32 s69, s40, 0x100
	v_mov_b32_e32 v0, 0
	s_addc_u32 s72, s41, 0
	s_mov_b32 s73, -2
	v_mov_b32_e32 v1, v0
	v_mov_b32_e32 v2, v0
	v_mov_b32_e32 v3, v0
	v_mov_b32_e32 v4, v0
	v_mov_b32_e32 v5, v0
	v_mov_b32_e32 v6, v0
	v_mov_b32_e32 v7, v0
	v_mov_b32_e32 v16, v0
	v_mov_b32_e32 v17, v0
	v_mov_b32_e32 v18, v0
	v_mov_b32_e32 v19, v0
	v_mov_b32_e32 v20, v0
	v_mov_b32_e32 v21, v0
	v_mov_b32_e32 v22, v0
	v_mov_b32_e32 v23, v0
	v_mov_b32_e32 v32, v0
	v_mov_b32_e32 v33, v0
	v_mov_b32_e32 v34, v0
	v_mov_b32_e32 v35, v0
	v_mov_b32_e32 v36, v0
	v_mov_b32_e32 v37, v0
	v_mov_b32_e32 v38, v0
	v_mov_b32_e32 v39, v0
	v_mov_b32_e32 v48, v0
	v_mov_b32_e32 v49, v0
	v_mov_b32_e32 v50, v0
	v_mov_b32_e32 v51, v0
	v_mov_b32_e32 v52, v0
	v_mov_b32_e32 v53, v0
	v_mov_b32_e32 v54, v0
	v_mov_b32_e32 v55, v0
	v_mov_b32_e32 v8, v0
	v_mov_b32_e32 v9, v0
	v_mov_b32_e32 v10, v0
	v_mov_b32_e32 v11, v0
	v_mov_b32_e32 v12, v0
	v_mov_b32_e32 v13, v0
	v_mov_b32_e32 v14, v0
	v_mov_b32_e32 v15, v0
	v_mov_b32_e32 v24, v0
	v_mov_b32_e32 v25, v0
	v_mov_b32_e32 v26, v0
	v_mov_b32_e32 v27, v0
	v_mov_b32_e32 v28, v0
	v_mov_b32_e32 v29, v0
	v_mov_b32_e32 v30, v0
	v_mov_b32_e32 v31, v0
	v_mov_b32_e32 v40, v0
	v_mov_b32_e32 v41, v0
	v_mov_b32_e32 v42, v0
	v_mov_b32_e32 v43, v0
	v_mov_b32_e32 v44, v0
	v_mov_b32_e32 v45, v0
	v_mov_b32_e32 v46, v0
	v_mov_b32_e32 v47, v0
	v_mov_b32_e32 v56, v0
	v_mov_b32_e32 v57, v0
	v_mov_b32_e32 v58, v0
	v_mov_b32_e32 v59, v0
	v_mov_b32_e32 v60, v0
	v_mov_b32_e32 v61, v0
	v_mov_b32_e32 v62, v0
	v_mov_b32_e32 v63, v0
	v_mov_b32_e32 v64, v0
	v_mov_b32_e32 v65, v0
	v_mov_b32_e32 v66, v0
	v_mov_b32_e32 v67, v0
	v_mov_b32_e32 v68, v0
	v_mov_b32_e32 v69, v0
	v_mov_b32_e32 v70, v0
	v_mov_b32_e32 v71, v0
	v_mov_b32_e32 v80, v0
	v_mov_b32_e32 v81, v0
	v_mov_b32_e32 v82, v0
	v_mov_b32_e32 v83, v0
	v_mov_b32_e32 v84, v0
	v_mov_b32_e32 v85, v0
	v_mov_b32_e32 v86, v0
	v_mov_b32_e32 v87, v0
	v_mov_b32_e32 v96, v0
	v_mov_b32_e32 v97, v0
	v_mov_b32_e32 v98, v0
	v_mov_b32_e32 v99, v0
	v_mov_b32_e32 v100, v0
	v_mov_b32_e32 v101, v0
	v_mov_b32_e32 v102, v0
	v_mov_b32_e32 v103, v0
	v_mov_b32_e32 v112, v0
	v_mov_b32_e32 v113, v0
	v_mov_b32_e32 v114, v0
	v_mov_b32_e32 v115, v0
	v_mov_b32_e32 v116, v0
	v_mov_b32_e32 v117, v0
	v_mov_b32_e32 v118, v0
	v_mov_b32_e32 v119, v0
	v_mov_b32_e32 v72, v0
	v_mov_b32_e32 v73, v0
	v_mov_b32_e32 v74, v0
	v_mov_b32_e32 v75, v0
	v_mov_b32_e32 v76, v0
	v_mov_b32_e32 v77, v0
	v_mov_b32_e32 v78, v0
	v_mov_b32_e32 v79, v0
	v_mov_b32_e32 v88, v0
	v_mov_b32_e32 v89, v0
	v_mov_b32_e32 v90, v0
	v_mov_b32_e32 v91, v0
	v_mov_b32_e32 v92, v0
	v_mov_b32_e32 v93, v0
	v_mov_b32_e32 v94, v0
	v_mov_b32_e32 v95, v0
	v_mov_b32_e32 v104, v0
	v_mov_b32_e32 v105, v0
	v_mov_b32_e32 v106, v0
	v_mov_b32_e32 v107, v0
	v_mov_b32_e32 v108, v0
	v_mov_b32_e32 v109, v0
	v_mov_b32_e32 v110, v0
	v_mov_b32_e32 v111, v0
	v_mov_b32_e32 v120, v0
	v_mov_b32_e32 v121, v0
	v_mov_b32_e32 v122, v0
	v_mov_b32_e32 v123, v0
	v_mov_b32_e32 v124, v0
	v_mov_b32_e32 v125, v0
	v_mov_b32_e32 v126, v0
	v_mov_b32_e32 v127, v0
	v_lshl_add_u32 v238, s8, 8, v248
	v_ashrrev_i32_e32 v239, 31, v238
	v_lshl_add_u64 v[238:239], v[238:239], 2, s[12:13]
	global_load_dword v240, v[238:239], off
	global_load_dword v241, v[238:239], off offset:64
	global_load_dword v242, v[238:239], off offset:128
	global_load_dword v243, v[238:239], off offset:192
	global_load_dword v244, v[238:239], off offset:512
	global_load_dword v245, v[238:239], off offset:576
	global_load_dword v246, v[238:239], off offset:640
	global_load_dword v247, v[238:239], off offset:704
	.p2align 6

; #define PG8_STAGE(bufoff, gbase, voff) do { _Pragma("unroll") for (int _i = 0; _i < 2; ++_i) \
;         __builtin_amdgcn_global_load_lds((const unsigned*)((const char*)(gbase) + (voff)[_i]), (PG8_LAS unsigned*)(lds + (bufoff) + ldsw + _i * 8192), 16, 0, 0); } while (0)
; #define PG8_WAIT_V(n) asm volatile("s_waitcnt vmcnt(" #n ")" ::: "memory")
; #define PG8_BAR __builtin_amdgcn_s_barrier()
; template <class Epi, class Sched, bool ALIGN_EPI = false, bool SP2 = false>
; __device__ __forceinline__ void gemm_phase(PG8_LAS unsigned char* lds, const Gemm g, const Sched& S, const Epi& E) {
;     const int tid = threadIdx.x, wid = __builtin_amdgcn_readfirstlane(tid >> 6), lane = tid & 63, wr = wid >> 2, wc = wid & 3, fr = lane & 15, fq = lane >> 4;
;     const int K = g.K, nt = K / BK;
;     unsigned voffA[2], voffB[2];
; #pragma unroll
;     for (int i = 0; i < 2; ++i) { int R, C; stage_rc(tid * 16 + i * 8192, R, C); const int Rb = Epi::PERM ? ((R & ~31) + perm32(R & 31)) : R;
;         voffA[i] = (unsigned)(R * K + C) * 2u; voffB[i] = (unsigned)(Rb * K + C) * 2u; }
;     const size_t kstep = (size_t)(BK * 2);
;     const size_t hstep = (size_t)HALF * K * 2;
;     const size_t tstep = 2 * hstep;
;     const unsigned ldsw = (unsigned)wid * 1024u;
;     const int aoff = lds_byte(wr * 64 + fr, fq * 8), boff = lds_byte(wc * 32 + fr, fq * 8);
;     ...
;     if constexpr (SP2) {
;         PG8_STAGE(PG8_SB(0, 0), cB, voffB); PG8_STAGE(PG8_SB(0, 1), cB + hstep, voffB); PG8_STAGE(PG8_SA(0, 0), cA, voffA); PG8_STAGE(PG8_SA(0, 1), cA + hstep, voffA);
;         if (wr == 1) PG8_BAR;
;         PG8_WAIT_V(2); PG8_BAR;
;         PG8_STAGE(PG8_SB(1, 0), cB + kstep, voffB); PG8_STAGE(PG8_SA(1, 0), cA + kstep, voffA); PG8_STAGE(PG8_SB(1, 1), cB + hstep + kstep, voffB);
;         PG8_WAIT_V(6); PG8_BAR;
.LBB0_815:
	s_lshl_b32 s18, s18, 5
	s_and_b32 s26, s18, 0x60
	s_mov_b64 s[18:19], 0x80
	s_add_i32 m0, s38, 0x18000
	v_lshl_add_u64 v[6:7], v[6:7], 0, s[18:19]
	s_lshl_b32 s23, s21, 13
	s_waitcnt vmcnt(2)
	s_barrier
	global_load_lds_dwordx4 v[6:7], off
	v_lshl_add_u64 v[4:5], v[4:5], 0, s[18:19]
	s_add_i32 m0, s38, 0x1a000
	s_add_i32 s45, s38, 0x8000
	s_add_i32 s60, s38, 0xa000
	global_load_lds_dwordx4 v[4:5], off
	v_lshl_add_u64 v[0:1], v[0:1], 0, s[18:19]
	s_mov_b32 m0, s45
	s_add_u32 s24, s8, 0xb0080
	global_load_lds_dwordx4 v[0:1], off
	v_lshl_add_u64 v[0:1], v[2:3], 0, s[18:19]
	s_mov_b32 m0, s60
	s_addc_u32 s25, s9, 0
	global_load_lds_dwordx4 v[0:1], off
	s_add_i32 m0, s38, 0x1c000
	v_lshl_add_u64 v[0:1], s[24:25], 0, v[132:133]
	global_load_lds_dwordx4 v[0:1], off
	v_lshl_add_u64 v[0:1], s[24:25], 0, v[128:129]
	s_add_i32 m0, s38, 0x1e000
	s_cmpk_lt_u32 s20, 0x100
	global_load_lds_dwordx4 v[0:1], off
	v_lshlrev_b32_e32 v1, 2, v189
	v_lshl_or_b32 v0, v189, 6, v190
	v_and_b32_e32 v1, 32, v1
	v_lshl_or_b32 v146, s21, 6, v189
	v_bitop3_b32 v0, v0, s23, v1 bitop3:0xde
	v_lshl_or_b32 v1, s26, 7, v191
	s_waitcnt vmcnt(6)
	s_cselect_b64 s[20:21], -1, 0
	v_add_u16_e32 v2, v186, v187
	s_add_i32 s63, 0, 0x10000
	s_add_i32 s65, 0, 0x14000
	s_add_i32 s67, 0, 0x18000
	s_add_i32 s69, 0, 0x1c000
	v_lshrrev_b16_e32 v2, 1, v2
	v_add_u32_e32 v148, s63, v1
	v_add_u32_e32 v149, s65, v1
	s_add_i32 s63, s63, s22
	s_add_i32 s65, s65, s22
	v_add_u32_e32 v151, s67, v1
	v_add_u32_e32 v152, s69, v1
	s_add_i32 s67, s67, s22
	s_add_i32 s69, s69, s22
	v_or_b32_e32 v147, s26, v188
	v_add_lshl_u32 v138, v9, v2, 1
	v_mov_b32_e32 v139, v137
	v_add_lshl_u32 v140, v8, v2, 1
	v_mov_b32_e32 v141, v137
	v_add_u32_e32 v150, 0, v0
	s_add_i32 s61, s38, 0xc000
	s_add_i32 s62, s38, 0xe000
	s_add_i32 s64, s63, 0x2000
	s_add_i32 s66, s65, 0x2000
	s_add_i32 s68, s67, 0x2000
	s_add_i32 s72, s69, 0x2000
	s_barrier
	s_branch .LBB0_818
	.p2align 6
.LBB0_816:
	s_mov_b64 s[22:23], 0
	.p2align 6

; template <class Epi, class Sched, bool ALIGN_EPI = false, bool SP2 = false>
; __device__ __forceinline__ void gemm_phase(PG8_LAS unsigned char* lds, const Gemm g, const Sched& S, const Epi& E) {
;     ...
;         const bool has_next = S.next(ui + 1, nxt);
;         const char* nA = has_next ? (const char*)g.A + (size_t)nxt.pm * tstep : cA; const char* nB = has_next ? (const char*)g.Bt + (size_t)nxt.pn * tstep : cB;
;         for (int t = 0; t < nt; t += 2) {
;             const bool last = (t == nt - 2);
;             const char* a1 = cA + (size_t)(t + 1) * kstep;
;             const char* a2 = last ? nA : cA + (size_t)(t + 2) * kstep; const char* b2 = last ? nB : cB + (size_t)(t + 2) * kstep;
;     ...
; #pragma unroll
;         for (int a = 0; a < 2; ++a)
; #pragma unroll
;             for (int b = 0; b < 2; ++b)
; #pragma unroll
;                 for (int m = 0; m < 4; ++m)
; #pragma unroll
;                     for (int n = 0; n < 2; ++n) acc[a][b][m][n] = (f32x4){0.f, 0.f, 0.f, 0.f};
;         cur = nxt; cA = nA; cB = nB; ++ui;
.LBB0_818:
	s_add_i32 s44, s44, 1
	s_mov_b64 s[26:27], s[8:9]
	s_mul_i32 s8, s44, s33
	s_add_i32 s8, s8, s70
	s_cmpk_lt_u32 s8, 0x60
	s_mov_b64 s[24:25], s[14:15]
	s_cselect_b64 s[22:23], -1, 0
	s_lshr_b32 s9, s8, 2
	s_and_b32 s14, s8, 3
	s_and_b32 s9, s9, 28
	s_or_b32 s14, s14, s48
	s_mov_b32 s74, s39
	s_add_i32 s39, s14, s9
	s_mov_b32 s73, s40
	s_bfe_u32 s40, s8, 0x20002
	s_mul_i32 s8, s39, 0x160000
	s_add_u32 s14, s46, s8
	s_addc_u32 s15, s47, 0
	s_and_b64 s[8:9], s[22:23], exec
	s_mul_i32 s8, s40, 0x160000
	s_cselect_b32 s75, s15, s25
	s_cselect_b32 s76, s14, s24
	s_add_u32 s8, s51, s8
	s_addc_u32 s9, s56, 0
	s_and_b64 s[36:37], s[22:23], exec
	s_cselect_b32 s77, s9, s27
	s_cselect_b32 s78, s8, s26
	s_add_u32 s24, s24, 0xb0080
	s_addc_u32 s25, s25, 0
	s_add_u32 s79, s26, 0x100
	v_mov_b32_e32 v0, 0
	s_addc_u32 s80, s27, 0
	s_mov_b32 s81, -2
	v_mov_b32_e32 v1, v0
	v_mov_b32_e32 v2, v0
	v_mov_b32_e32 v3, v0
	v_mov_b32_e32 v4, v0
	v_mov_b32_e32 v5, v0
	v_mov_b32_e32 v6, v0
	v_mov_b32_e32 v7, v0
	s_waitcnt vmcnt(0)
	v_mov_b32_e32 v16, v0
	v_mov_b32_e32 v17, v0
	v_mov_b32_e32 v18, v0
	v_mov_b32_e32 v19, v0
	v_mov_b32_e32 v20, v0
	v_mov_b32_e32 v21, v0
	v_mov_b32_e32 v22, v0
	v_mov_b32_e32 v23, v0
	v_mov_b32_e32 v32, v0
	v_mov_b32_e32 v33, v0
	v_mov_b32_e32 v34, v0
	v_mov_b32_e32 v35, v0
	v_mov_b32_e32 v36, v0
	v_mov_b32_e32 v37, v0
	v_mov_b32_e32 v38, v0
	v_mov_b32_e32 v39, v0
	v_mov_b32_e32 v48, v0
	v_mov_b32_e32 v49, v0
	v_mov_b32_e32 v50, v0
	v_mov_b32_e32 v51, v0
	v_mov_b32_e32 v52, v0
	v_mov_b32_e32 v53, v0
	v_mov_b32_e32 v54, v0
	v_mov_b32_e32 v55, v0
	v_mov_b32_e32 v8, v0
	v_mov_b32_e32 v9, v0
	v_mov_b32_e32 v10, v0
	v_mov_b32_e32 v11, v0
	v_mov_b32_e32 v12, v0
	v_mov_b32_e32 v13, v0
	v_mov_b32_e32 v14, v0
	v_mov_b32_e32 v15, v0
	v_mov_b32_e32 v24, v0
	v_mov_b32_e32 v25, v0
	v_mov_b32_e32 v26, v0
	v_mov_b32_e32 v27, v0
	v_mov_b32_e32 v28, v0
	v_mov_b32_e32 v29, v0
	v_mov_b32_e32 v30, v0
	v_mov_b32_e32 v31, v0
	v_mov_b32_e32 v40, v0
	v_mov_b32_e32 v41, v0
	v_mov_b32_e32 v42, v0
	v_mov_b32_e32 v43, v0
	v_mov_b32_e32 v44, v0
	v_mov_b32_e32 v45, v0
	v_mov_b32_e32 v46, v0
	v_mov_b32_e32 v47, v0
	v_mov_b32_e32 v56, v0
	v_mov_b32_e32 v57, v0
	v_mov_b32_e32 v58, v0
	v_mov_b32_e32 v59, v0
	v_mov_b32_e32 v60, v0
	v_mov_b32_e32 v61, v0
	v_mov_b32_e32 v62, v0
	v_mov_b32_e32 v63, v0
	v_mov_b32_e32 v64, v0
	v_mov_b32_e32 v65, v0
	v_mov_b32_e32 v66, v0
	v_mov_b32_e32 v67, v0
	v_mov_b32_e32 v68, v0
	v_mov_b32_e32 v69, v0
	v_mov_b32_e32 v70, v0
	v_mov_b32_e32 v71, v0
	v_mov_b32_e32 v80, v0
	v_mov_b32_e32 v81, v0
	v_mov_b32_e32 v82, v0
	v_mov_b32_e32 v83, v0
	v_mov_b32_e32 v84, v0
	v_mov_b32_e32 v85, v0
	v_mov_b32_e32 v86, v0
	v_mov_b32_e32 v87, v0
	v_mov_b32_e32 v96, v0
	v_mov_b32_e32 v97, v0
	v_mov_b32_e32 v98, v0
	v_mov_b32_e32 v99, v0
	v_mov_b32_e32 v100, v0
	v_mov_b32_e32 v101, v0
	v_mov_b32_e32 v102, v0
	v_mov_b32_e32 v103, v0
	v_mov_b32_e32 v112, v0
	v_mov_b32_e32 v113, v0
	v_mov_b32_e32 v114, v0
	v_mov_b32_e32 v115, v0
	v_mov_b32_e32 v116, v0
	v_mov_b32_e32 v117, v0
	v_mov_b32_e32 v118, v0
	v_mov_b32_e32 v119, v0
	v_mov_b32_e32 v72, v0
	v_mov_b32_e32 v73, v0
	v_mov_b32_e32 v74, v0
	v_mov_b32_e32 v75, v0
	v_mov_b32_e32 v76, v0
	v_mov_b32_e32 v77, v0
	v_mov_b32_e32 v78, v0
	v_mov_b32_e32 v79, v0
	v_mov_b32_e32 v88, v0
	v_mov_b32_e32 v89, v0
	v_mov_b32_e32 v90, v0
	v_mov_b32_e32 v91, v0
	v_mov_b32_e32 v92, v0
	v_mov_b32_e32 v93, v0
	v_mov_b32_e32 v94, v0
	v_mov_b32_e32 v95, v0
	v_mov_b32_e32 v104, v0
	v_mov_b32_e32 v105, v0
	v_mov_b32_e32 v106, v0
	v_mov_b32_e32 v107, v0
	v_mov_b32_e32 v108, v0
	v_mov_b32_e32 v109, v0
	v_mov_b32_e32 v110, v0
	v_mov_b32_e32 v111, v0
	v_mov_b32_e32 v120, v0
	v_mov_b32_e32 v121, v0
	v_mov_b32_e32 v122, v0
	v_mov_b32_e32 v123, v0
	v_mov_b32_e32 v124, v0
	v_mov_b32_e32 v125, v0
	v_mov_b32_e32 v126, v0
	v_mov_b32_e32 v127, v0
	.p2align 6

; #define PG8_STAGE(bufoff, gbase, voff) do { _Pragma("unroll") for (int _i = 0; _i < 2; ++_i) \
;         __builtin_amdgcn_global_load_lds((const unsigned*)((const char*)(gbase) + (voff)[_i]), (PG8_LAS unsigned*)(lds + (bufoff) + ldsw + _i * 8192), 16, 0, 0); } while (0)
; #define PG8_WAIT_V(n) asm volatile("s_waitcnt vmcnt(" #n ")" ::: "memory")
; #define PG8_BAR __builtin_amdgcn_s_barrier()
; template <class Epi, class Sched, bool ALIGN_EPI = false, bool SP2 = false>
; __device__ __forceinline__ void gemm_phase(PG8_LAS unsigned char* lds, const Gemm g, const Sched& S, const Epi& E) {
;     const int tid = threadIdx.x, wid = __builtin_amdgcn_readfirstlane(tid >> 6), lane = tid & 63, wr = wid >> 2, wc = wid & 3, fr = lane & 15, fq = lane >> 4;
;     const int K = g.K, nt = K / BK;
;     unsigned voffA[2], voffB[2];
; #pragma unroll
;     for (int i = 0; i < 2; ++i) { int R, C; stage_rc(tid * 16 + i * 8192, R, C); const int Rb = Epi::PERM ? ((R & ~31) + perm32(R & 31)) : R;
;         voffA[i] = (unsigned)(R * K + C) * 2u; voffB[i] = (unsigned)(Rb * K + C) * 2u; }
;     const size_t kstep = (size_t)(BK * 2);
;     const size_t hstep = (size_t)HALF * K * 2;
;     const size_t tstep = 2 * hstep;
;     const unsigned ldsw = (unsigned)wid * 1024u;
;     const int aoff = lds_byte(wr * 64 + fr, fq * 8), boff = lds_byte(wc * 32 + fr, fq * 8);
;     ...
;     if constexpr (SP2) {
;         PG8_STAGE(PG8_SB(0, 0), cB, voffB); PG8_STAGE(PG8_SB(0, 1), cB + hstep, voffB); PG8_STAGE(PG8_SA(0, 0), cA, voffA); PG8_STAGE(PG8_SA(0, 1), cA + hstep, voffA);
;         if (wr == 1) PG8_BAR;
;         PG8_WAIT_V(2); PG8_BAR;
;         PG8_STAGE(PG8_SB(1, 0), cB + kstep, voffB); PG8_STAGE(PG8_SA(1, 0), cA + kstep, voffA); PG8_STAGE(PG8_SB(1, 1), cB + hstep + kstep, voffB);
;         PG8_WAIT_V(6); PG8_BAR;
.LBB0_837:
	s_add_u32 s16, s28, 0x3e550000
	s_addc_u32 s17, s29, 0
	s_lshl_b32 s18, s18, 5
	s_and_b32 s24, s18, 0x60
	s_mov_b64 s[18:19], 0x80
	s_add_i32 m0, s61, 0x18000
	v_lshl_add_u64 v[6:7], v[6:7], 0, s[18:19]
	s_lshl_b32 s9, s21, 13
	s_waitcnt vmcnt(2)
	s_barrier
	global_load_lds_dwordx4 v[6:7], off
	v_lshl_add_u64 v[4:5], v[4:5], 0, s[18:19]
	s_add_i32 m0, s61, 0x1a000
	s_add_i32 s66, s61, 0x8000
	s_add_i32 s67, s61, 0xa000
	global_load_lds_dwordx4 v[4:5], off
	v_lshl_add_u64 v[0:1], v[0:1], 0, s[18:19]
	s_mov_b32 m0, s66
	s_add_u32 s22, s42, 0x40080
	global_load_lds_dwordx4 v[0:1], off
	v_lshl_add_u64 v[0:1], v[2:3], 0, s[18:19]
	s_mov_b32 m0, s67
	s_addc_u32 s23, s43, 0
	global_load_lds_dwordx4 v[0:1], off
	s_add_i32 m0, s61, 0x1c000
	v_lshl_add_u64 v[0:1], s[22:23], 0, v[178:179]
	global_load_lds_dwordx4 v[0:1], off
	v_lshl_add_u64 v[0:1], s[22:23], 0, v[182:183]
	s_add_i32 m0, s61, 0x1e000
	v_lshlrev_b32_e32 v2, 11, v197
	global_load_lds_dwordx4 v[0:1], off
	v_lshlrev_b32_e32 v1, 2, v189
	v_lshl_or_b32 v0, v189, 6, v190
	v_and_b32_e32 v1, 32, v1
	v_bitop3_b32 v0, v0, s9, v1 bitop3:0xde
	v_lshlrev_b32_e32 v1, 8, v192
	v_and_b32_e32 v1, 0x38000, v1
	v_or3_b32 v1, v186, v1, v2
	v_add_u32_e32 v128, v1, v187
	v_lshlrev_b32_e32 v1, 4, v198
	s_waitcnt vmcnt(6)
	s_cmpk_lt_u32 s20, 0x100
	v_and_b32_e32 v1, 0x78000, v1
	v_lshl_or_b32 v248, s21, 6, v189
	v_lshl_add_u32 v249, v188, 1, v189
	v_lshrrev_b32_e32 v250, 2, v249
	v_and_b32_e32 v251, 3, v249
	v_lshl_or_b32 v140, s21, 6, v250
	v_lshl_add_u32 v249, v251, 4, v250
	v_lshlrev_b32_e32 v249, 2, v249
	v_lshl_or_b32 v141, s24, 7, v191
	s_cselect_b64 s[20:21], -1, 0
	v_or3_b32 v1, v186, v1, v2
	s_add_i32 s68, 0, 0x10000
	s_add_i32 s69, 0, 0x14000
	v_lshl_or_b32 v142, v251, 3, s24
	v_mov_b32_e32 v129, v179
	v_add_u32_e32 v130, v1, v187
	v_mov_b32_e32 v131, v179
	v_add_u32_e32 v143, s68, v141
	v_add_u32_e32 v146, s69, v141
	v_add_u32_e32 v147, 0, v0
	s_movk_i32 s71, 0x2b00
	s_movk_i32 s72, 0x1580
	v_mov_b32_e32 v148, 0x358637bd
	s_mov_b32 s73, 0x800000
	s_barrier
	s_branch .LBB0_840
	.p2align 6
.LBB0_838:
	s_mov_b64 s[2:3], 0
	.p2align 6

; template <class Epi, class Sched, bool ALIGN_EPI = false, bool SP2 = false>
; __device__ __forceinline__ void gemm_phase(PG8_LAS unsigned char* lds, const Gemm g, const Sched& S, const Epi& E) {
;     ...
; #pragma unroll
;         for (int a = 0; a < 2; ++a)
; #pragma unroll
;             for (int b = 0; b < 2; ++b)
; #pragma unroll
;                 for (int m = 0; m < 4; ++m)
; #pragma unroll
;                     for (int n = 0; n < 2; ++n) acc[a][b][m][n] = (f32x4){0.f, 0.f, 0.f, 0.f};
;         cur = nxt; cA = nA; cB = nB; ++ui;
.LBB0_842:
	s_ashr_i32 s23, s22, 31
	s_lshl_b64 s[26:27], s[22:23], 19
	s_add_u32 s26, s58, s26
	s_addc_u32 s27, s59, s27
	s_and_b64 s[38:39], s[36:37], exec
	s_cselect_b32 s9, s27, s3
	s_cselect_b32 s23, s26, s2
	s_ashr_i32 s25, s24, 31
	s_lshl_b64 s[38:39], s[24:25], 19
	s_add_u32 s38, s49, s38
	s_addc_u32 s39, s50, s39
	s_and_b64 s[44:45], s[36:37], exec
	s_cselect_b32 s25, s39, s43
	s_cselect_b32 s41, s38, s42
	s_add_u32 s2, s2, 0x40080
	s_addc_u32 s3, s3, 0
	s_add_u32 s74, s42, 0x100
	v_mov_b32_e32 v0, 0
	s_addc_u32 s75, s43, 0
	s_mov_b32 s76, -2
	v_mov_b32_e32 v1, v0
	v_mov_b32_e32 v2, v0
	v_mov_b32_e32 v3, v0
	v_mov_b32_e32 v4, v0
	v_mov_b32_e32 v5, v0
	v_mov_b32_e32 v6, v0
	v_mov_b32_e32 v7, v0
	v_mov_b32_e32 v16, v0
	v_mov_b32_e32 v17, v0
	v_mov_b32_e32 v18, v0
	v_mov_b32_e32 v19, v0
	v_mov_b32_e32 v20, v0
	v_mov_b32_e32 v21, v0
	v_mov_b32_e32 v22, v0
	v_mov_b32_e32 v23, v0
	v_mov_b32_e32 v32, v0
	v_mov_b32_e32 v33, v0
	v_mov_b32_e32 v34, v0
	v_mov_b32_e32 v35, v0
	v_mov_b32_e32 v36, v0
	v_mov_b32_e32 v37, v0
	v_mov_b32_e32 v38, v0
	v_mov_b32_e32 v39, v0
	v_mov_b32_e32 v48, v0
	v_mov_b32_e32 v49, v0
	v_mov_b32_e32 v50, v0
	v_mov_b32_e32 v51, v0
	v_mov_b32_e32 v52, v0
	v_mov_b32_e32 v53, v0
	v_mov_b32_e32 v54, v0
	v_mov_b32_e32 v55, v0
	v_mov_b32_e32 v8, v0
	v_mov_b32_e32 v9, v0
	v_mov_b32_e32 v10, v0
	v_mov_b32_e32 v11, v0
	v_mov_b32_e32 v12, v0
	v_mov_b32_e32 v13, v0
	v_mov_b32_e32 v14, v0
	v_mov_b32_e32 v15, v0
	v_mov_b32_e32 v24, v0
	v_mov_b32_e32 v25, v0
	v_mov_b32_e32 v26, v0
	v_mov_b32_e32 v27, v0
	v_mov_b32_e32 v28, v0
	v_mov_b32_e32 v29, v0
	v_mov_b32_e32 v30, v0
	v_mov_b32_e32 v31, v0
	v_mov_b32_e32 v40, v0
	v_mov_b32_e32 v41, v0
	v_mov_b32_e32 v42, v0
	v_mov_b32_e32 v43, v0
	v_mov_b32_e32 v44, v0
	v_mov_b32_e32 v45, v0
	v_mov_b32_e32 v46, v0
	v_mov_b32_e32 v47, v0
	v_mov_b32_e32 v56, v0
	v_mov_b32_e32 v57, v0
	v_mov_b32_e32 v58, v0
	v_mov_b32_e32 v59, v0
	v_mov_b32_e32 v60, v0
	v_mov_b32_e32 v61, v0
	v_mov_b32_e32 v62, v0
	v_mov_b32_e32 v63, v0
	v_mov_b32_e32 v64, v0
	v_mov_b32_e32 v65, v0
	v_mov_b32_e32 v66, v0
	v_mov_b32_e32 v67, v0
	v_mov_b32_e32 v68, v0
	v_mov_b32_e32 v69, v0
	v_mov_b32_e32 v70, v0
	v_mov_b32_e32 v71, v0
	v_mov_b32_e32 v80, v0
	v_mov_b32_e32 v81, v0
	v_mov_b32_e32 v82, v0
	v_mov_b32_e32 v83, v0
	v_mov_b32_e32 v84, v0
	v_mov_b32_e32 v85, v0
	v_mov_b32_e32 v86, v0
	v_mov_b32_e32 v87, v0
	v_mov_b32_e32 v96, v0
	v_mov_b32_e32 v97, v0
	v_mov_b32_e32 v98, v0
	v_mov_b32_e32 v99, v0
	v_mov_b32_e32 v100, v0
	v_mov_b32_e32 v101, v0
	v_mov_b32_e32 v102, v0
	v_mov_b32_e32 v103, v0
	v_mov_b32_e32 v112, v0
	v_mov_b32_e32 v113, v0
	v_mov_b32_e32 v114, v0
	v_mov_b32_e32 v115, v0
	v_mov_b32_e32 v116, v0
	v_mov_b32_e32 v117, v0
	v_mov_b32_e32 v118, v0
	v_mov_b32_e32 v119, v0
	v_mov_b32_e32 v72, v0
	v_mov_b32_e32 v73, v0
	v_mov_b32_e32 v74, v0
	v_mov_b32_e32 v75, v0
	v_mov_b32_e32 v76, v0
	v_mov_b32_e32 v77, v0
	v_mov_b32_e32 v78, v0
	v_mov_b32_e32 v79, v0
	v_mov_b32_e32 v88, v0
	v_mov_b32_e32 v89, v0
	v_mov_b32_e32 v90, v0
	v_mov_b32_e32 v91, v0
	v_mov_b32_e32 v92, v0
	v_mov_b32_e32 v93, v0
	v_mov_b32_e32 v94, v0
	v_mov_b32_e32 v95, v0
	v_mov_b32_e32 v104, v0
	v_mov_b32_e32 v105, v0
	v_mov_b32_e32 v106, v0
	v_mov_b32_e32 v107, v0
	v_mov_b32_e32 v108, v0
	v_mov_b32_e32 v109, v0
	v_mov_b32_e32 v110, v0
	v_mov_b32_e32 v111, v0
	v_mov_b32_e32 v120, v0
	v_mov_b32_e32 v121, v0
	v_mov_b32_e32 v122, v0
	v_mov_b32_e32 v123, v0
	v_mov_b32_e32 v124, v0
	v_mov_b32_e32 v125, v0
	v_mov_b32_e32 v126, v0
	v_mov_b32_e32 v127, v0
	v_lshl_add_u32 v238, s40, 8, v248
	v_ashrrev_i32_e32 v239, 31, v238
	v_lshl_add_u64 v[238:239], v[238:239], 2, s[16:17]
	global_load_dword v240, v[238:239], off
	global_load_dword v241, v[238:239], off offset:64
	global_load_dword v242, v[238:239], off offset:128
	global_load_dword v243, v[238:239], off offset:192
	global_load_dword v244, v[238:239], off offset:512
	global_load_dword v245, v[238:239], off offset:576
	global_load_dword v246, v[238:239], off offset:640
	global_load_dword v247, v[238:239], off offset:704
	.p2align 6

; #define PG8_STAGE(bufoff, gbase, voff) do { _Pragma("unroll") for (int _i = 0; _i < 2; ++_i) \
;         __builtin_amdgcn_global_load_lds((const unsigned*)((const char*)(gbase) + (voff)[_i]), (PG8_LAS unsigned*)(lds + (bufoff) + ldsw + _i * 8192), 16, 0, 0); } while (0)
; #define PG8_WAIT_V(n) asm volatile("s_waitcnt vmcnt(" #n ")" ::: "memory")
; #define PG8_BAR __builtin_amdgcn_s_barrier()
; template <class Epi, class Sched, bool ALIGN_EPI = false, bool SP2 = false>
; __device__ __forceinline__ void gemm_phase(PG8_LAS unsigned char* lds, const Gemm g, const Sched& S, const Epi& E) {
;     const int tid = threadIdx.x, wid = __builtin_amdgcn_readfirstlane(tid >> 6), lane = tid & 63, wr = wid >> 2, wc = wid & 3, fr = lane & 15, fq = lane >> 4;
;     const int K = g.K, nt = K / BK;
;     unsigned voffA[2], voffB[2];
; #pragma unroll
;     for (int i = 0; i < 2; ++i) { int R, C; stage_rc(tid * 16 + i * 8192, R, C); const int Rb = Epi::PERM ? ((R & ~31) + perm32(R & 31)) : R;
;         voffA[i] = (unsigned)(R * K + C) * 2u; voffB[i] = (unsigned)(Rb * K + C) * 2u; }
;     const size_t kstep = (size_t)(BK * 2);
;     const size_t hstep = (size_t)HALF * K * 2;
;     const size_t tstep = 2 * hstep;
;     const unsigned ldsw = (unsigned)wid * 1024u;
;     const int aoff = lds_byte(wr * 64 + fr, fq * 8), boff = lds_byte(wc * 32 + fr, fq * 8);
;     ...
;     if constexpr (SP2) {
;         PG8_STAGE(PG8_SB(0, 0), cB, voffB); PG8_STAGE(PG8_SB(0, 1), cB + hstep, voffB); PG8_STAGE(PG8_SA(0, 0), cA, voffA); PG8_STAGE(PG8_SA(0, 1), cA + hstep, voffA);
;         if (wr == 1) PG8_BAR;
;         PG8_WAIT_V(2); PG8_BAR;
;         PG8_STAGE(PG8_SB(1, 0), cB + kstep, voffB); PG8_STAGE(PG8_SA(1, 0), cA + kstep, voffA); PG8_STAGE(PG8_SB(1, 1), cB + hstep + kstep, voffB);
;         PG8_WAIT_V(6); PG8_BAR;
.LBB0_919:
	s_lshl_b32 s6, s7, 5
	s_and_b32 s14, s6, 0x60
	s_mov_b64 s[6:7], 0x80
	s_add_i32 m0, s18, 0x18000
	v_lshl_add_u64 v[6:7], v[6:7], 0, s[6:7]
	s_lshl_b32 s11, s9, 13
	s_waitcnt vmcnt(2)
	s_barrier
	global_load_lds_dwordx4 v[6:7], off
	v_lshl_add_u64 v[4:5], v[4:5], 0, s[6:7]
	s_add_i32 m0, s18, 0x1a000
	s_add_i32 s25, s18, 0x8000
	s_add_i32 s26, s18, 0xa000
	global_load_lds_dwordx4 v[4:5], off
	v_lshl_add_u64 v[0:1], v[0:1], 0, s[6:7]
	s_mov_b32 m0, s25
	s_add_u32 s12, s0, 0xb0080
	global_load_lds_dwordx4 v[0:1], off
	v_lshl_add_u64 v[0:1], v[2:3], 0, s[6:7]
	s_mov_b32 m0, s26
	s_addc_u32 s13, s1, 0
	global_load_lds_dwordx4 v[0:1], off
	s_add_i32 m0, s18, 0x1c000
	v_lshl_add_u64 v[0:1], s[12:13], 0, v[132:133]
	global_load_lds_dwordx4 v[0:1], off
	v_lshl_add_u64 v[0:1], s[12:13], 0, v[128:129]
	s_add_i32 m0, s18, 0x1e000
	s_cmpk_lt_u32 s8, 0x100
	global_load_lds_dwordx4 v[0:1], off
	v_lshlrev_b32_e32 v1, 2, v189
	v_lshl_or_b32 v0, v189, 6, v190
	v_and_b32_e32 v1, 32, v1
	v_lshl_or_b32 v144, s9, 6, v189
	v_bitop3_b32 v0, v0, s11, v1 bitop3:0xde
	v_lshl_or_b32 v1, s14, 7, v191
	s_waitcnt vmcnt(6)
	s_cselect_b64 s[8:9], -1, 0
	v_add_u16_e32 v2, v186, v187
	s_add_i32 s29, 0, 0x10000
	s_add_i32 s35, 0, 0x14000
	s_add_i32 s37, 0, 0x18000
	s_add_i32 s39, 0, 0x1c000
	v_lshrrev_b16_e32 v2, 1, v2
	v_add_u32_e32 v146, s29, v1
	v_add_u32_e32 v147, s35, v1
	s_add_i32 s29, s29, s10
	s_add_i32 s35, s35, s10
	v_add_u32_e32 v149, s37, v1
	v_add_u32_e32 v150, s39, v1
	s_add_i32 s37, s37, s10
	s_add_i32 s39, s39, s10
	v_or_b32_e32 v145, s14, v188
	v_add_lshl_u32 v138, v9, v2, 1
	v_mov_b32_e32 v139, v137
	v_add_lshl_u32 v140, v8, v2, 1
	v_mov_b32_e32 v141, v137
	v_add_u32_e32 v148, 0, v0
	s_add_i32 s27, s18, 0xc000
	s_add_i32 s28, s18, 0xe000
	s_add_i32 s34, s29, 0x2000
	s_add_i32 s36, s35, 0x2000
	s_add_i32 s38, s37, 0x2000
	s_add_i32 s40, s39, 0x2000
	s_barrier
	s_branch .LBB0_922
	.p2align 6
.LBB0_920:
	s_mov_b64 s[10:11], 0
	.p2align 6

; template <class Epi, class Sched, bool ALIGN_EPI = false, bool SP2 = false>
; __device__ __forceinline__ void gemm_phase(PG8_LAS unsigned char* lds, const Gemm g, const Sched& S, const Epi& E) {
;     ...
;         const bool has_next = S.next(ui + 1, nxt);
;         const char* nA = has_next ? (const char*)g.A + (size_t)nxt.pm * tstep : cA; const char* nB = has_next ? (const char*)g.Bt + (size_t)nxt.pn * tstep : cB;
;         for (int t = 0; t < nt; t += 2) {
;             const bool last = (t == nt - 2);
;             const char* a1 = cA + (size_t)(t + 1) * kstep;
;             const char* a2 = last ? nA : cA + (size_t)(t + 2) * kstep; const char* b2 = last ? nB : cB + (size_t)(t + 2) * kstep;
;     ...
; #pragma unroll
;         for (int a = 0; a < 2; ++a)
; #pragma unroll
;             for (int b = 0; b < 2; ++b)
; #pragma unroll
;                 for (int m = 0; m < 4; ++m)
; #pragma unroll
;                     for (int n = 0; n < 2; ++n) acc[a][b][m][n] = (f32x4){0.f, 0.f, 0.f, 0.f};
;         cur = nxt; cA = nA; cB = nB; ++ui;
.LBB0_922:
	s_add_i32 s24, s24, 1
	s_mov_b64 s[14:15], s[0:1]
	s_mul_i32 s0, s24, s33
	s_add_i32 s0, s0, s70
	s_cmpk_lt_u32 s0, 0x60
	s_mov_b64 s[12:13], s[2:3]
	s_cselect_b64 s[10:11], -1, 0
	s_lshr_b32 s1, s0, 2
	s_and_b32 s2, s0, 3
	s_and_b32 s1, s1, 28
	s_or_b32 s2, s2, s48
	s_mov_b32 s42, s19
	s_add_i32 s19, s2, s1
	s_mov_b32 s41, s20
	s_bfe_u32 s20, s0, 0x20002
	s_mul_i32 s0, s19, 0x160000
	s_add_u32 s2, s46, s0
	s_addc_u32 s3, s47, 0
	s_and_b64 s[0:1], s[10:11], exec
	s_mul_i32 s0, s20, 0x160000
	s_cselect_b32 s43, s3, s13
	s_cselect_b32 s44, s2, s12
	s_add_u32 s0, s51, s0
	s_addc_u32 s1, s56, 0
	s_and_b64 s[16:17], s[10:11], exec
	s_cselect_b32 s45, s1, s15
	s_cselect_b32 s49, s0, s14
	s_add_u32 s12, s12, 0xb0080
	s_addc_u32 s13, s13, 0
	s_add_u32 s50, s14, 0x100
	v_mov_b32_e32 v0, 0
	s_addc_u32 s52, s15, 0
	s_mov_b32 s53, -2
	v_mov_b32_e32 v1, v0
	v_mov_b32_e32 v2, v0
	v_mov_b32_e32 v3, v0
	v_mov_b32_e32 v4, v0
	v_mov_b32_e32 v5, v0
	v_mov_b32_e32 v6, v0
	v_mov_b32_e32 v7, v0
	s_waitcnt vmcnt(0)
	v_mov_b32_e32 v16, v0
	v_mov_b32_e32 v17, v0
	v_mov_b32_e32 v18, v0
	v_mov_b32_e32 v19, v0
	v_mov_b32_e32 v20, v0
	v_mov_b32_e32 v21, v0
	v_mov_b32_e32 v22, v0
	v_mov_b32_e32 v23, v0
	v_mov_b32_e32 v32, v0
	v_mov_b32_e32 v33, v0
	v_mov_b32_e32 v34, v0
	v_mov_b32_e32 v35, v0
	v_mov_b32_e32 v36, v0
	v_mov_b32_e32 v37, v0
	v_mov_b32_e32 v38, v0
	v_mov_b32_e32 v39, v0
	v_mov_b32_e32 v48, v0
	v_mov_b32_e32 v49, v0
	v_mov_b32_e32 v50, v0
	v_mov_b32_e32 v51, v0
	v_mov_b32_e32 v52, v0
	v_mov_b32_e32 v53, v0
	v_mov_b32_e32 v54, v0
	v_mov_b32_e32 v55, v0
	v_mov_b32_e32 v8, v0
	v_mov_b32_e32 v9, v0
	v_mov_b32_e32 v10, v0
	v_mov_b32_e32 v11, v0
	v_mov_b32_e32 v12, v0
	v_mov_b32_e32 v13, v0
	v_mov_b32_e32 v14, v0
	v_mov_b32_e32 v15, v0
	v_mov_b32_e32 v24, v0
	v_mov_b32_e32 v25, v0
	v_mov_b32_e32 v26, v0
	v_mov_b32_e32 v27, v0
	v_mov_b32_e32 v28, v0
	v_mov_b32_e32 v29, v0
	v_mov_b32_e32 v30, v0
	v_mov_b32_e32 v31, v0
	v_mov_b32_e32 v40, v0
	v_mov_b32_e32 v41, v0
	v_mov_b32_e32 v42, v0
	v_mov_b32_e32 v43, v0
	v_mov_b32_e32 v44, v0
	v_mov_b32_e32 v45, v0
	v_mov_b32_e32 v46, v0
	v_mov_b32_e32 v47, v0
	v_mov_b32_e32 v56, v0
	v_mov_b32_e32 v57, v0
	v_mov_b32_e32 v58, v0
	v_mov_b32_e32 v59, v0
	v_mov_b32_e32 v60, v0
	v_mov_b32_e32 v61, v0
	v_mov_b32_e32 v62, v0
	v_mov_b32_e32 v63, v0
	v_mov_b32_e32 v64, v0
	v_mov_b32_e32 v65, v0
	v_mov_b32_e32 v66, v0
	v_mov_b32_e32 v67, v0
	v_mov_b32_e32 v68, v0
	v_mov_b32_e32 v69, v0
	v_mov_b32_e32 v70, v0
	v_mov_b32_e32 v71, v0
	v_mov_b32_e32 v80, v0
	v_mov_b32_e32 v81, v0
	v_mov_b32_e32 v82, v0
	v_mov_b32_e32 v83, v0
	v_mov_b32_e32 v84, v0
	v_mov_b32_e32 v85, v0
	v_mov_b32_e32 v86, v0
	v_mov_b32_e32 v87, v0
	v_mov_b32_e32 v96, v0
	v_mov_b32_e32 v97, v0
	v_mov_b32_e32 v98, v0
	v_mov_b32_e32 v99, v0
	v_mov_b32_e32 v100, v0
	v_mov_b32_e32 v101, v0
	v_mov_b32_e32 v102, v0
	v_mov_b32_e32 v103, v0
	v_mov_b32_e32 v112, v0
	v_mov_b32_e32 v113, v0
	v_mov_b32_e32 v114, v0
	v_mov_b32_e32 v115, v0
	v_mov_b32_e32 v116, v0
	v_mov_b32_e32 v117, v0
	v_mov_b32_e32 v118, v0
	v_mov_b32_e32 v119, v0
	v_mov_b32_e32 v72, v0
	v_mov_b32_e32 v73, v0
	v_mov_b32_e32 v74, v0
	v_mov_b32_e32 v75, v0
	v_mov_b32_e32 v76, v0
	v_mov_b32_e32 v77, v0
	v_mov_b32_e32 v78, v0
	v_mov_b32_e32 v79, v0
	v_mov_b32_e32 v88, v0
	v_mov_b32_e32 v89, v0
	v_mov_b32_e32 v90, v0
	v_mov_b32_e32 v91, v0
	v_mov_b32_e32 v92, v0
	v_mov_b32_e32 v93, v0
	v_mov_b32_e32 v94, v0
	v_mov_b32_e32 v95, v0
	v_mov_b32_e32 v104, v0
	v_mov_b32_e32 v105, v0
	v_mov_b32_e32 v106, v0
	v_mov_b32_e32 v107, v0
	v_mov_b32_e32 v108, v0
	v_mov_b32_e32 v109, v0
	v_mov_b32_e32 v110, v0
	v_mov_b32_e32 v111, v0
	v_mov_b32_e32 v120, v0
	v_mov_b32_e32 v121, v0
	v_mov_b32_e32 v122, v0
	v_mov_b32_e32 v123, v0
	v_mov_b32_e32 v124, v0
	v_mov_b32_e32 v125, v0
	v_mov_b32_e32 v126, v0
	v_mov_b32_e32 v127, v0
	.p2align 6
